# v18: write-through (sc1) stores in all GEMM epilogues (H, U, X) so the barrier's L2 write-back has little left to do; on top of v16
# baseline (speedup 1.0000x reference)
; DI unsigned cvt_pk(float lo, float hi) { unsigned r; asm("v_cvt_pk_bf16_f32 %0, %1, %2" : "=v"(r) : "v"(lo), "v"(hi)); return r; }
;     __device__ __forceinline__ void operator()(const f32x4 (&acc)[2][2][4][2], const Unit& u, int wr, int wc, int fr, int fq) const {
;     ...
;                 for (int mm = 0; mm < 2; ++mm) {
;                     const int m = mp * 2 + mm;
;                     const int row = row0 + ai * HALF + m * 16;
;                     float s = 0.f;
; #pragma unroll
;                     for (int bj = 0; bj < 2; ++bj) {
;                         u32x4* px = (u32x4*)(X + (size_t)row * DM + col0 + bj * HALF);
;                         float xo[8]; unpack8(xin[mm][bj], xo);
;                         const f32x4 a0 = acc[ai][bj][m][0] + pv[mm][bj][0], a1 = acc[ai][bj][m][1] + pv[mm][bj][1];
;                         u32x4 w;
;                         w.x = cvt_pk(xo[0] + scale * a0[0], xo[1] + scale * a0[1]); w.y = cvt_pk(xo[2] + scale * a0[2], xo[3] + scale * a0[3]);
;                         w.z = cvt_pk(xo[4] + scale * a1[0], xo[5] + scale * a1[1]); w.w = cvt_pk(xo[6] + scale * a1[2], xo[7] + scale * a1[3]);
;                         *px = w;
;                         float xn[8]; unpack8(w, xn);
; #pragma unroll
;                         for (int j = 0; j < 8; ++j) s += xn[j] * xn[j];
;                     }
;                     s += __shfl_xor(s, 16); s += __shfl_xor(s, 32);
;                     if (fq == 0) unsafeAtomicAdd(ssn + row, s);
.LBB0_405:
	s_or_b64 exec, exec, s[12:13]
	s_waitcnt vmcnt(0)
	v_lshlrev_b32_e32 v210, 16, v140
	v_and_b32_e32 v211, 0xffff0000, v140
	v_lshlrev_b32_e32 v214, 16, v141
	v_and_b32_e32 v215, 0xffff0000, v141
	v_and_b32_e32 v238, 0xffff0000, v142
	v_pk_add_f32 v[140:141], v[124:125], v[206:207]
	v_pk_add_f32 v[202:203], v[120:121], v[202:203]
	v_lshlrev_b32_e32 v237, 16, v142
	v_fmac_f32_e32 v210, 0.5, v140
	v_fmac_f32_e32 v211, 0.5, v141
	v_cvt_pk_bf16_f32 v140, v210, v211
	v_fmac_f32_e32 v238, 0.5, v203
	v_and_b32_e32 v203, 0xffff0000, v140
	v_lshlrev_b32_e32 v244, 16, v143
	v_and_b32_e32 v245, 0xffff0000, v143
	v_pk_add_f32 v[142:143], v[126:127], v[208:209]
	v_pk_add_f32 v[204:205], v[122:123], v[204:205]
	v_fmac_f32_e32 v237, 0.5, v202
	v_lshlrev_b32_e32 v202, 16, v140
	v_mul_f32_e32 v203, v203, v203
	v_fmac_f32_e32 v214, 0.5, v142
	v_fmac_f32_e32 v215, 0.5, v143
	v_cvt_pk_bf16_f32 v141, v214, v215
	v_fmac_f32_e32 v244, 0.5, v204
	v_lshlrev_b32_e32 v204, 16, v141
	v_fmac_f32_e32 v203, v202, v202
	v_fmac_f32_e32 v245, 0.5, v205
	v_and_b32_e32 v205, 0xffff0000, v141
	v_fmac_f32_e32 v203, v204, v204
	v_cvt_pk_bf16_f32 v142, v237, v238
	v_fmac_f32_e32 v203, v205, v205
	v_lshlrev_b32_e32 v206, 16, v142
	v_and_b32_e32 v207, 0xffff0000, v142
	v_fmac_f32_e32 v203, v206, v206
	v_cvt_pk_bf16_f32 v143, v244, v245
	v_fmac_f32_e32 v203, v207, v207
	v_lshlrev_b32_e32 v208, 16, v143
	v_and_b32_e32 v209, 0xffff0000, v143
	v_fmac_f32_e32 v203, v208, v208
	v_fmac_f32_e32 v203, v209, v209
	v_lshlrev_b32_e32 v202, 16, v136
	v_and_b32_e32 v204, 0xffff0000, v136
	v_lshlrev_b32_e32 v205, 16, v137
	v_and_b32_e32 v206, 0xffff0000, v137
	v_lshlrev_b32_e32 v207, 16, v138
	v_and_b32_e32 v208, 0xffff0000, v138
	v_lshlrev_b32_e32 v209, 16, v139
	v_and_b32_e32 v210, 0xffff0000, v139
	v_pk_add_f32 v[136:137], v[94:95], v[200:201]
	v_pk_add_f32 v[138:139], v[92:93], v[198:199]
	v_pk_add_f32 v[198:199], v[90:91], v[196:197]
	v_pk_add_f32 v[196:197], v[88:89], v[194:195]
	v_fmac_f32_e32 v202, 0.5, v138
	v_fmac_f32_e32 v204, 0.5, v139
	v_cvt_pk_bf16_f32 v194, v202, v204
	v_fmac_f32_e32 v205, 0.5, v136
	v_lshlrev_b32_e32 v136, 16, v194
	v_fmac_f32_e32 v206, 0.5, v137
	v_and_b32_e32 v137, 0xffff0000, v194
	v_fmac_f32_e32 v203, v136, v136
	v_cvt_pk_bf16_f32 v195, v205, v206
	v_fmac_f32_e32 v203, v137, v137
	v_lshlrev_b32_e32 v138, 16, v195
	v_and_b32_e32 v139, 0xffff0000, v195
	v_fmac_f32_e32 v203, v138, v138
	v_fmac_f32_e32 v207, 0.5, v196
	v_fmac_f32_e32 v208, 0.5, v197
	v_cvt_pk_bf16_f32 v196, v207, v208
	v_fmac_f32_e32 v209, 0.5, v198
	v_lshlrev_b32_e32 v198, 16, v196
	v_fmac_f32_e32 v203, v139, v139
	v_and_b32_e32 v137, 64, v221
	v_fmac_f32_e32 v210, 0.5, v199
	v_and_b32_e32 v199, 0xffff0000, v196
	v_fmac_f32_e32 v203, v198, v198
	v_xor_b32_e32 v136, 16, v221
	v_add_u32_e32 v137, 64, v137
	v_cvt_pk_bf16_f32 v197, v209, v210
	v_fmac_f32_e32 v203, v199, v199
	v_lshlrev_b32_e32 v200, 16, v197
	v_cmp_lt_i32_e64 s[12:13], v136, v137
	v_and_b32_e32 v201, 0xffff0000, v197
	v_fmac_f32_e32 v203, v200, v200
	v_cndmask_b32_e64 v136, v221, v136, s[12:13]
	v_fmac_f32_e32 v203, v201, v201
	v_lshlrev_b32_e32 v237, 2, v136
	ds_bpermute_b32 v136, v237, v203
	v_xor_b32_e32 v138, 32, v221
	v_cmp_lt_i32_e64 s[12:13], v138, v137
	s_waitcnt lgkmcnt(0)
	v_add_f32_e32 v136, v203, v136
	v_cndmask_b32_e64 v137, v221, v138, s[12:13]
	v_lshlrev_b32_e32 v238, 2, v137
	ds_bpermute_b32 v137, v238, v136
	v_lshl_add_u64 v[138:139], s[28:29], 0, v[174:175]
	v_lshl_add_u64 v[138:139], v[168:169], 1, v[138:139]
	global_store_dwordx4 v[138:139], v[140:143], off sc1
	global_store_dwordx4 v[138:139], v[194:197], off offset:256 sc1
	s_and_saveexec_b64 s[12:13], s[8:9]
	s_cbranch_execz .LBB0_407
	s_waitcnt lgkmcnt(0)
	v_add_f32_e32 v138, v136, v137
	v_lshl_add_u64 v[136:137], v[166:167], 2, s[6:7]
	global_atomic_add_f32 v[136:137], v138, off
; DI unsigned cvt_pk(float lo, float hi) { unsigned r; asm("v_cvt_pk_bf16_f32 %0, %1, %2" : "=v"(r) : "v"(lo), "v"(hi)); return r; }
;     __device__ __forceinline__ void operator()(const f32x4 (&acc)[2][2][4][2], const Unit& u, int wr, int wc, int fr, int fq) const {
;     ...
;                 for (int mm = 0; mm < 2; ++mm) {
;                     const int m = mp * 2 + mm;
;                     const int row = row0 + ai * HALF + m * 16;
;                     float s = 0.f;
; #pragma unroll
;                     for (int bj = 0; bj < 2; ++bj) {
;                         u32x4* px = (u32x4*)(X + (size_t)row * DM + col0 + bj * HALF);
;                         float xo[8]; unpack8(xin[mm][bj], xo);
;                         const f32x4 a0 = acc[ai][bj][m][0] + pv[mm][bj][0], a1 = acc[ai][bj][m][1] + pv[mm][bj][1];
;                         u32x4 w;
;                         w.x = cvt_pk(xo[0] + scale * a0[0], xo[1] + scale * a0[1]); w.y = cvt_pk(xo[2] + scale * a0[2], xo[3] + scale * a0[3]);
;                         w.z = cvt_pk(xo[4] + scale * a1[0], xo[5] + scale * a1[1]); w.w = cvt_pk(xo[6] + scale * a1[2], xo[7] + scale * a1[3]);
;                         *px = w;
;                         float xn[8]; unpack8(w, xn);
; #pragma unroll
;                         for (int j = 0; j < 8; ++j) s += xn[j] * xn[j];
;                     }
;                     s += __shfl_xor(s, 16); s += __shfl_xor(s, 32);
;                     if (fq == 0) unsafeAtomicAdd(ssn + row, s);
.LBB0_407:
	s_or_b64 exec, exec, s[12:13]
	v_lshlrev_b32_e32 v140, 16, v132
	v_and_b32_e32 v141, 0xffff0000, v132
	v_lshlrev_b32_e32 v142, 16, v133
	v_and_b32_e32 v143, 0xffff0000, v133
	v_and_b32_e32 v197, 0xffff0000, v135
	v_pk_add_f32 v[132:133], v[116:117], v[190:191]
	s_waitcnt lgkmcnt(0)
	v_pk_add_f32 v[136:137], v[114:115], v[188:189]
	v_lshlrev_b32_e32 v196, 16, v135
	v_fmac_f32_e32 v140, 0.5, v132
	v_fmac_f32_e32 v141, 0.5, v133
	v_cvt_pk_bf16_f32 v132, v140, v141
	v_fmac_f32_e32 v197, 0.5, v137
	v_and_b32_e32 v137, 0xffff0000, v132
	v_lshlrev_b32_e32 v194, 16, v134
	v_and_b32_e32 v195, 0xffff0000, v134
	v_pk_add_f32 v[134:135], v[118:119], v[192:193]
	v_pk_add_f32 v[138:139], v[112:113], v[186:187]
	v_fmac_f32_e32 v196, 0.5, v136
	v_lshlrev_b32_e32 v136, 16, v132
	v_mul_f32_e32 v186, v137, v137
	v_fmac_f32_e32 v142, 0.5, v134
	v_fmac_f32_e32 v143, 0.5, v135
	v_cvt_pk_bf16_f32 v133, v142, v143
	v_fmac_f32_e32 v194, 0.5, v138
	v_lshlrev_b32_e32 v138, 16, v133
	v_fmac_f32_e32 v186, v136, v136
	v_fmac_f32_e32 v195, 0.5, v139
	v_and_b32_e32 v139, 0xffff0000, v133
	v_fmac_f32_e32 v186, v138, v138
	v_cvt_pk_bf16_f32 v134, v194, v195
	v_fmac_f32_e32 v186, v139, v139
	v_lshlrev_b32_e32 v140, 16, v134
	v_and_b32_e32 v141, 0xffff0000, v134
	v_fmac_f32_e32 v186, v140, v140
	v_cvt_pk_bf16_f32 v135, v196, v197
	v_fmac_f32_e32 v186, v141, v141
	v_lshlrev_b32_e32 v142, 16, v135
	v_and_b32_e32 v143, 0xffff0000, v135
	v_fmac_f32_e32 v186, v142, v142
	v_lshlrev_b32_e32 v136, 16, v128
	v_lshlrev_b32_e32 v187, 16, v130
	v_and_b32_e32 v188, 0xffff0000, v130
	v_lshlrev_b32_e32 v189, 16, v131
	v_and_b32_e32 v190, 0xffff0000, v131
	v_pk_add_f32 v[130:131], v[84:85], v[182:183]
	v_fmac_f32_e32 v186, v143, v143
	v_and_b32_e32 v137, 0xffff0000, v128
	v_lshlrev_b32_e32 v142, 16, v129
	v_and_b32_e32 v143, 0xffff0000, v129
	v_pk_add_f32 v[128:129], v[86:87], v[184:185]
	v_fmac_f32_e32 v136, 0.5, v130
	v_fmac_f32_e32 v137, 0.5, v131
	v_cvt_pk_bf16_f32 v136, v136, v137
	v_fmac_f32_e32 v142, 0.5, v128
	v_lshlrev_b32_e32 v128, 16, v136
	v_fmac_f32_e32 v143, 0.5, v129
	v_and_b32_e32 v129, 0xffff0000, v136
	v_fmac_f32_e32 v186, v128, v128
	v_cvt_pk_bf16_f32 v137, v142, v143
	v_fmac_f32_e32 v186, v129, v129
	v_lshlrev_b32_e32 v130, 16, v137
	v_pk_add_f32 v[140:141], v[82:83], v[180:181]
	v_pk_add_f32 v[138:139], v[80:81], v[178:179]
	v_and_b32_e32 v131, 0xffff0000, v137
	v_fmac_f32_e32 v186, v130, v130
	v_fmac_f32_e32 v187, 0.5, v138
	v_fmac_f32_e32 v188, 0.5, v139
	v_cvt_pk_bf16_f32 v138, v187, v188
	v_fmac_f32_e32 v189, 0.5, v140
	v_lshlrev_b32_e32 v140, 16, v138
	v_fmac_f32_e32 v186, v131, v131
	v_fmac_f32_e32 v190, 0.5, v141
	v_and_b32_e32 v141, 0xffff0000, v138
	v_fmac_f32_e32 v186, v140, v140
	v_cvt_pk_bf16_f32 v139, v189, v190
	v_fmac_f32_e32 v186, v141, v141
	v_lshlrev_b32_e32 v142, 16, v139
	v_and_b32_e32 v143, 0xffff0000, v139
	v_fmac_f32_e32 v186, v142, v142
	v_fmac_f32_e32 v186, v143, v143
	ds_bpermute_b32 v128, v237, v186
	v_lshl_add_u64 v[130:131], s[28:29], 0, v[176:177]
	v_lshl_add_u64 v[130:131], v[168:169], 1, v[130:131]
	global_store_dwordx4 v[130:131], v[132:135], off sc1
	global_store_dwordx4 v[130:131], v[136:139], off offset:256 sc1
	s_waitcnt lgkmcnt(0)
	v_add_f32_e32 v128, v186, v128
	ds_bpermute_b32 v129, v238, v128
	s_and_saveexec_b64 s[12:13], s[8:9]
	s_cbranch_execz .LBB0_409
	s_waitcnt lgkmcnt(0)
	v_add_f32_e32 v130, v128, v129
	v_lshl_add_u64 v[128:129], v[166:167], 2, s[6:7]
	global_atomic_add_f32 v[128:129], v130, off offset:64

; DI unsigned cvt_pk(float lo, float hi) { unsigned r; asm("v_cvt_pk_bf16_f32 %0, %1, %2" : "=v"(r) : "v"(lo), "v"(hi)); return r; }
;     __device__ __forceinline__ void operator()(const f32x4 (&acc)[2][2][4][2], const Unit& u, int wr, int wc, int fr, int fq) const {
;     ...
;                 for (int mm = 0; mm < 2; ++mm) {
;                     const int m = mp * 2 + mm;
;                     const int row = row0 + ai * HALF + m * 16;
;                     float s = 0.f;
; #pragma unroll
;                     for (int bj = 0; bj < 2; ++bj) {
;                         u32x4* px = (u32x4*)(X + (size_t)row * DM + col0 + bj * HALF);
;                         float xo[8]; unpack8(xin[mm][bj], xo);
;                         const f32x4 a0 = acc[ai][bj][m][0] + pv[mm][bj][0], a1 = acc[ai][bj][m][1] + pv[mm][bj][1];
;                         u32x4 w;
;                         w.x = cvt_pk(xo[0] + scale * a0[0], xo[1] + scale * a0[1]); w.y = cvt_pk(xo[2] + scale * a0[2], xo[3] + scale * a0[3]);
;                         w.z = cvt_pk(xo[4] + scale * a1[0], xo[5] + scale * a1[1]); w.w = cvt_pk(xo[6] + scale * a1[2], xo[7] + scale * a1[3]);
;                         *px = w;
;                         float xn[8]; unpack8(w, xn);
; #pragma unroll
;                         for (int j = 0; j < 8; ++j) s += xn[j] * xn[j];
;                     }
;                     s += __shfl_xor(s, 16); s += __shfl_xor(s, 32);
;                     if (fq == 0) unsafeAtomicAdd(ssn + row, s);
.LBB0_411:
	s_or_b64 exec, exec, s[12:13]
	s_waitcnt vmcnt(3)
	v_lshlrev_b32_e32 v214, 16, v140
	v_and_b32_e32 v215, 0xffff0000, v140
	v_lshlrev_b32_e32 v244, 16, v141
	v_and_b32_e32 v245, 0xffff0000, v141
	v_and_b32_e32 v247, 0xffff0000, v142
	v_pk_add_f32 v[140:141], v[108:109], v[208:209]
	v_pk_add_f32 v[204:205], v[104:105], v[204:205]
	v_lshlrev_b32_e32 v246, 16, v142
	v_fmac_f32_e32 v214, 0.5, v140
	v_fmac_f32_e32 v215, 0.5, v141
	v_cvt_pk_bf16_f32 v140, v214, v215
	v_fmac_f32_e32 v247, 0.5, v205
	v_and_b32_e32 v205, 0xffff0000, v140
	v_lshlrev_b32_e32 v248, 16, v143
	v_and_b32_e32 v249, 0xffff0000, v143
	v_pk_add_f32 v[142:143], v[110:111], v[210:211]
	v_pk_add_f32 v[206:207], v[106:107], v[206:207]
	v_fmac_f32_e32 v246, 0.5, v204
	v_lshlrev_b32_e32 v204, 16, v140
	v_mul_f32_e32 v205, v205, v205
	v_fmac_f32_e32 v244, 0.5, v142
	v_fmac_f32_e32 v245, 0.5, v143
	v_cvt_pk_bf16_f32 v141, v244, v245
	v_fmac_f32_e32 v248, 0.5, v206
	v_lshlrev_b32_e32 v206, 16, v141
	v_fmac_f32_e32 v205, v204, v204
	v_fmac_f32_e32 v249, 0.5, v207
	v_and_b32_e32 v207, 0xffff0000, v141
	v_fmac_f32_e32 v205, v206, v206
	v_cvt_pk_bf16_f32 v142, v246, v247
	v_fmac_f32_e32 v205, v207, v207
	v_lshlrev_b32_e32 v208, 16, v142
	v_and_b32_e32 v209, 0xffff0000, v142
	v_fmac_f32_e32 v205, v208, v208
	v_cvt_pk_bf16_f32 v143, v248, v249
	v_fmac_f32_e32 v205, v209, v209
	v_lshlrev_b32_e32 v210, 16, v143
	v_and_b32_e32 v211, 0xffff0000, v143
	v_fmac_f32_e32 v205, v210, v210
	v_fmac_f32_e32 v205, v211, v211
	s_waitcnt vmcnt(2)
	v_lshlrev_b32_e32 v204, 16, v136
	v_and_b32_e32 v206, 0xffff0000, v136
	v_lshlrev_b32_e32 v207, 16, v137
	v_and_b32_e32 v208, 0xffff0000, v137
	v_lshlrev_b32_e32 v209, 16, v138
	v_and_b32_e32 v210, 0xffff0000, v138
	v_lshlrev_b32_e32 v211, 16, v139
	v_and_b32_e32 v214, 0xffff0000, v139
	v_pk_add_f32 v[136:137], v[78:79], v[202:203]
	v_pk_add_f32 v[138:139], v[76:77], v[200:201]
	v_pk_add_f32 v[200:201], v[74:75], v[198:199]
	v_pk_add_f32 v[198:199], v[72:73], v[196:197]
	v_fmac_f32_e32 v204, 0.5, v138
	v_fmac_f32_e32 v206, 0.5, v139
	v_cvt_pk_bf16_f32 v196, v204, v206
	v_fmac_f32_e32 v207, 0.5, v136
	v_lshlrev_b32_e32 v136, 16, v196
	v_fmac_f32_e32 v208, 0.5, v137
	v_and_b32_e32 v137, 0xffff0000, v196
	v_fmac_f32_e32 v205, v136, v136
	v_cvt_pk_bf16_f32 v197, v207, v208
	v_fmac_f32_e32 v205, v137, v137
	v_lshlrev_b32_e32 v138, 16, v197
	v_and_b32_e32 v139, 0xffff0000, v197
	v_fmac_f32_e32 v205, v138, v138
	v_fmac_f32_e32 v209, 0.5, v198
	v_fmac_f32_e32 v210, 0.5, v199
	v_cvt_pk_bf16_f32 v198, v209, v210
	v_fmac_f32_e32 v211, 0.5, v200
	v_lshlrev_b32_e32 v200, 16, v198
	v_fmac_f32_e32 v205, v139, v139
	v_fmac_f32_e32 v214, 0.5, v201
	v_and_b32_e32 v201, 0xffff0000, v198
	v_fmac_f32_e32 v205, v200, v200
	v_cvt_pk_bf16_f32 v199, v211, v214
	v_fmac_f32_e32 v205, v201, v201
	v_lshlrev_b32_e32 v202, 16, v199
	v_and_b32_e32 v203, 0xffff0000, v199
	v_fmac_f32_e32 v205, v202, v202
	v_fmac_f32_e32 v205, v203, v203
	ds_bpermute_b32 v136, v237, v205
	v_lshl_add_u64 v[138:139], s[28:29], 0, v[186:187]
	v_lshl_add_u64 v[138:139], v[168:169], 1, v[138:139]
	global_store_dwordx4 v[138:139], v[140:143], off sc1
	global_store_dwordx4 v[138:139], v[196:199], off offset:256 sc1
	s_waitcnt lgkmcnt(0)
	v_add_f32_e32 v136, v205, v136
	ds_bpermute_b32 v137, v238, v136
	s_and_saveexec_b64 s[12:13], s[8:9]
	s_cbranch_execz .LBB0_413
	s_waitcnt lgkmcnt(0)
	v_add_f32_e32 v138, v136, v137
	v_lshl_add_u64 v[136:137], v[166:167], 2, s[6:7]
	global_atomic_add_f32 v[136:137], v138, off offset:128
.LBB0_413:
	s_or_b64 exec, exec, s[12:13]
	s_waitcnt vmcnt(3)
	v_lshlrev_b32_e32 v140, 16, v132
	v_and_b32_e32 v141, 0xffff0000, v132
	v_lshlrev_b32_e32 v142, 16, v133
	v_and_b32_e32 v143, 0xffff0000, v133
	v_lshlrev_b32_e32 v186, 16, v134
	v_and_b32_e32 v197, 0xffff0000, v135
	v_pk_add_f32 v[132:133], v[100:101], v[192:193]
	s_waitcnt lgkmcnt(0)
	v_pk_add_f32 v[136:137], v[98:99], v[190:191]
	v_pk_add_f32 v[138:139], v[96:97], v[188:189]
	v_and_b32_e32 v187, 0xffff0000, v134
	v_lshlrev_b32_e32 v196, 16, v135
	v_pk_add_f32 v[134:135], v[102:103], v[194:195]
	v_fmac_f32_e32 v140, 0.5, v132
	v_fmac_f32_e32 v141, 0.5, v133
	v_cvt_pk_bf16_f32 v132, v140, v141
	v_fmac_f32_e32 v186, 0.5, v138
	v_fmac_f32_e32 v197, 0.5, v137
	v_and_b32_e32 v137, 0xffff0000, v132
	v_fmac_f32_e32 v142, 0.5, v134
	v_fmac_f32_e32 v187, 0.5, v139
	v_cvt_pk_bf16_f32 v134, v186, v187
	v_fmac_f32_e32 v196, 0.5, v136
	v_lshlrev_b32_e32 v136, 16, v132
	v_mul_f32_e32 v186, v137, v137
	v_fmac_f32_e32 v143, 0.5, v135
	v_cvt_pk_bf16_f32 v133, v142, v143
	v_fmac_f32_e32 v186, v136, v136
	v_lshlrev_b32_e32 v138, 16, v133
	v_and_b32_e32 v139, 0xffff0000, v133
	v_fmac_f32_e32 v186, v138, v138
	v_lshlrev_b32_e32 v140, 16, v134
	v_fmac_f32_e32 v186, v139, v139
	v_and_b32_e32 v141, 0xffff0000, v134
	v_fmac_f32_e32 v186, v140, v140
	v_cvt_pk_bf16_f32 v135, v196, v197
	v_fmac_f32_e32 v186, v141, v141
	v_lshlrev_b32_e32 v142, 16, v135
	v_and_b32_e32 v143, 0xffff0000, v135
	v_fmac_f32_e32 v186, v142, v142
	s_waitcnt vmcnt(2)
	v_lshlrev_b32_e32 v136, 16, v128
	v_lshlrev_b32_e32 v187, 16, v130
	v_and_b32_e32 v188, 0xffff0000, v130
	v_lshlrev_b32_e32 v189, 16, v131
	v_and_b32_e32 v190, 0xffff0000, v131
	v_pk_add_f32 v[130:131], v[68:69], v[182:183]
	v_fmac_f32_e32 v186, v143, v143
	v_and_b32_e32 v137, 0xffff0000, v128
	v_lshlrev_b32_e32 v142, 16, v129
	v_and_b32_e32 v143, 0xffff0000, v129
	v_pk_add_f32 v[128:129], v[70:71], v[184:185]
	v_fmac_f32_e32 v136, 0.5, v130
	v_fmac_f32_e32 v137, 0.5, v131
	v_cvt_pk_bf16_f32 v136, v136, v137
	v_fmac_f32_e32 v142, 0.5, v128
	v_lshlrev_b32_e32 v128, 16, v136
	v_fmac_f32_e32 v143, 0.5, v129
	v_and_b32_e32 v129, 0xffff0000, v136
	v_fmac_f32_e32 v186, v128, v128
	v_cvt_pk_bf16_f32 v137, v142, v143
	v_fmac_f32_e32 v186, v129, v129
	v_lshlrev_b32_e32 v130, 16, v137
	v_pk_add_f32 v[140:141], v[66:67], v[180:181]
	v_pk_add_f32 v[138:139], v[64:65], v[178:179]
	v_and_b32_e32 v131, 0xffff0000, v137
	v_fmac_f32_e32 v186, v130, v130
	v_fmac_f32_e32 v187, 0.5, v138
	v_fmac_f32_e32 v188, 0.5, v139
	v_cvt_pk_bf16_f32 v138, v187, v188
	v_fmac_f32_e32 v189, 0.5, v140
	v_lshlrev_b32_e32 v140, 16, v138
	v_fmac_f32_e32 v186, v131, v131
	v_fmac_f32_e32 v190, 0.5, v141
	v_and_b32_e32 v141, 0xffff0000, v138
	v_fmac_f32_e32 v186, v140, v140
	v_cvt_pk_bf16_f32 v139, v189, v190
	v_fmac_f32_e32 v186, v141, v141
	v_lshlrev_b32_e32 v142, 16, v139
	v_and_b32_e32 v143, 0xffff0000, v139
	v_fmac_f32_e32 v186, v142, v142
	v_fmac_f32_e32 v186, v143, v143
	ds_bpermute_b32 v128, v237, v186
	v_lshl_add_u64 v[130:131], s[28:29], 0, v[176:177]
	v_lshl_add_u64 v[130:131], v[168:169], 1, v[130:131]
	global_store_dwordx4 v[130:131], v[132:135], off sc1
	global_store_dwordx4 v[130:131], v[136:139], off offset:256 sc1
	s_waitcnt lgkmcnt(0)
	v_add_f32_e32 v128, v186, v128
	ds_bpermute_b32 v129, v238, v128
	s_and_saveexec_b64 s[12:13], s[8:9]
	s_cbranch_execz .LBB0_415
	s_waitcnt lgkmcnt(0)
	v_add_f32_e32 v130, v128, v129
	v_lshl_add_u64 v[128:129], v[166:167], 2, s[6:7]
	global_atomic_add_f32 v[128:129], v130, off offset:192

; DI unsigned cvt_pk(float lo, float hi) { unsigned r; asm("v_cvt_pk_bf16_f32 %0, %1, %2" : "=v"(r) : "v"(lo), "v"(hi)); return r; }
;     __device__ __forceinline__ void operator()(const f32x4 (&acc)[2][2][4][2], const Unit& u, int wr, int wc, int fr, int fq) const {
;     ...
;                 for (int mm = 0; mm < 2; ++mm) {
;                     const int m = mp * 2 + mm;
;                     const int row = row0 + ai * HALF + m * 16;
;                     float s = 0.f;
; #pragma unroll
;                     for (int bj = 0; bj < 2; ++bj) {
;                         u32x4* px = (u32x4*)(X + (size_t)row * DM + col0 + bj * HALF);
;                         float xo[8]; unpack8(xin[mm][bj], xo);
;                         const f32x4 a0 = acc[ai][bj][m][0] + pv[mm][bj][0], a1 = acc[ai][bj][m][1] + pv[mm][bj][1];
;                         u32x4 w;
;                         w.x = cvt_pk(xo[0] + scale * a0[0], xo[1] + scale * a0[1]); w.y = cvt_pk(xo[2] + scale * a0[2], xo[3] + scale * a0[3]);
;                         w.z = cvt_pk(xo[4] + scale * a1[0], xo[5] + scale * a1[1]); w.w = cvt_pk(xo[6] + scale * a1[2], xo[7] + scale * a1[3]);
;                         *px = w;
;                         float xn[8]; unpack8(w, xn);
; #pragma unroll
;                         for (int j = 0; j < 8; ++j) s += xn[j] * xn[j];
;                     }
;                     s += __shfl_xor(s, 16); s += __shfl_xor(s, 32);
;                     if (fq == 0) unsafeAtomicAdd(ssn + row, s);
.LBB0_417:
	s_or_b64 exec, exec, s[12:13]
	s_waitcnt vmcnt(3)
	v_lshlrev_b32_e32 v214, 16, v140
	v_and_b32_e32 v215, 0xffff0000, v140
	v_lshlrev_b32_e32 v244, 16, v141
	v_and_b32_e32 v245, 0xffff0000, v141
	v_and_b32_e32 v247, 0xffff0000, v142
	v_pk_add_f32 v[140:141], v[60:61], v[208:209]
	v_pk_add_f32 v[204:205], v[56:57], v[204:205]
	v_lshlrev_b32_e32 v246, 16, v142
	v_fmac_f32_e32 v214, 0.5, v140
	v_fmac_f32_e32 v215, 0.5, v141
	v_cvt_pk_bf16_f32 v140, v214, v215
	v_fmac_f32_e32 v247, 0.5, v205
	v_and_b32_e32 v205, 0xffff0000, v140
	v_lshlrev_b32_e32 v248, 16, v143
	v_and_b32_e32 v249, 0xffff0000, v143
	v_pk_add_f32 v[142:143], v[62:63], v[210:211]
	v_pk_add_f32 v[206:207], v[58:59], v[206:207]
	v_fmac_f32_e32 v246, 0.5, v204
	v_lshlrev_b32_e32 v204, 16, v140
	v_mul_f32_e32 v205, v205, v205
	v_fmac_f32_e32 v244, 0.5, v142
	v_fmac_f32_e32 v245, 0.5, v143
	v_cvt_pk_bf16_f32 v141, v244, v245
	v_fmac_f32_e32 v248, 0.5, v206
	v_lshlrev_b32_e32 v206, 16, v141
	v_fmac_f32_e32 v205, v204, v204
	v_fmac_f32_e32 v249, 0.5, v207
	v_and_b32_e32 v207, 0xffff0000, v141
	v_fmac_f32_e32 v205, v206, v206
	v_cvt_pk_bf16_f32 v142, v246, v247
	v_fmac_f32_e32 v205, v207, v207
	v_lshlrev_b32_e32 v208, 16, v142
	v_and_b32_e32 v209, 0xffff0000, v142
	v_fmac_f32_e32 v205, v208, v208
	v_cvt_pk_bf16_f32 v143, v248, v249
	v_fmac_f32_e32 v205, v209, v209
	v_lshlrev_b32_e32 v210, 16, v143
	v_and_b32_e32 v211, 0xffff0000, v143
	v_fmac_f32_e32 v205, v210, v210
	v_fmac_f32_e32 v205, v211, v211
	s_waitcnt vmcnt(2)
	v_lshlrev_b32_e32 v204, 16, v136
	v_and_b32_e32 v206, 0xffff0000, v136
	v_lshlrev_b32_e32 v207, 16, v137
	v_and_b32_e32 v208, 0xffff0000, v137
	v_lshlrev_b32_e32 v209, 16, v138
	v_and_b32_e32 v210, 0xffff0000, v138
	v_lshlrev_b32_e32 v211, 16, v139
	v_and_b32_e32 v214, 0xffff0000, v139
	v_pk_add_f32 v[136:137], v[30:31], v[202:203]
	v_pk_add_f32 v[138:139], v[28:29], v[200:201]
	v_pk_add_f32 v[200:201], v[26:27], v[198:199]
	v_pk_add_f32 v[198:199], v[24:25], v[196:197]
	v_fmac_f32_e32 v204, 0.5, v138
	v_fmac_f32_e32 v206, 0.5, v139
	v_cvt_pk_bf16_f32 v196, v204, v206
	v_fmac_f32_e32 v207, 0.5, v136
	v_lshlrev_b32_e32 v136, 16, v196
	v_fmac_f32_e32 v208, 0.5, v137
	v_and_b32_e32 v137, 0xffff0000, v196
	v_fmac_f32_e32 v205, v136, v136
	v_cvt_pk_bf16_f32 v197, v207, v208
	v_fmac_f32_e32 v205, v137, v137
	v_lshlrev_b32_e32 v138, 16, v197
	v_and_b32_e32 v139, 0xffff0000, v197
	v_fmac_f32_e32 v205, v138, v138
	v_fmac_f32_e32 v209, 0.5, v198
	v_fmac_f32_e32 v210, 0.5, v199
	v_cvt_pk_bf16_f32 v198, v209, v210
	v_fmac_f32_e32 v211, 0.5, v200
	v_lshlrev_b32_e32 v200, 16, v198
	v_fmac_f32_e32 v205, v139, v139
	v_fmac_f32_e32 v214, 0.5, v201
	v_and_b32_e32 v201, 0xffff0000, v198
	v_fmac_f32_e32 v205, v200, v200
	v_cvt_pk_bf16_f32 v199, v211, v214
	v_fmac_f32_e32 v205, v201, v201
	v_lshlrev_b32_e32 v202, 16, v199
	v_and_b32_e32 v203, 0xffff0000, v199
	v_fmac_f32_e32 v205, v202, v202
	v_fmac_f32_e32 v205, v203, v203
	ds_bpermute_b32 v136, v237, v205
	v_lshl_add_u64 v[138:139], s[28:29], 0, v[186:187]
	v_lshl_add_u64 v[138:139], v[168:169], 1, v[138:139]
	global_store_dwordx4 v[138:139], v[140:143], off sc1
	global_store_dwordx4 v[138:139], v[196:199], off offset:256 sc1
	s_waitcnt lgkmcnt(0)
	v_add_f32_e32 v136, v205, v136
	ds_bpermute_b32 v137, v238, v136
	s_and_saveexec_b64 s[12:13], s[8:9]
	s_cbranch_execz .LBB0_419
	s_waitcnt lgkmcnt(0)
	v_add_f32_e32 v138, v136, v137
	v_lshl_add_u64 v[136:137], v[166:167], 2, s[6:7]
	global_atomic_add_f32 v[136:137], v138, off offset:512
.LBB0_419:
	s_or_b64 exec, exec, s[12:13]
	s_waitcnt vmcnt(3)
	v_lshlrev_b32_e32 v140, 16, v132
	v_and_b32_e32 v141, 0xffff0000, v132
	v_lshlrev_b32_e32 v142, 16, v133
	v_and_b32_e32 v143, 0xffff0000, v133
	v_lshlrev_b32_e32 v186, 16, v134
	v_and_b32_e32 v197, 0xffff0000, v135
	v_pk_add_f32 v[132:133], v[52:53], v[192:193]
	s_waitcnt lgkmcnt(0)
	v_pk_add_f32 v[136:137], v[50:51], v[190:191]
	v_pk_add_f32 v[138:139], v[48:49], v[188:189]
	v_and_b32_e32 v187, 0xffff0000, v134
	v_lshlrev_b32_e32 v196, 16, v135
	v_pk_add_f32 v[134:135], v[54:55], v[194:195]
	v_fmac_f32_e32 v140, 0.5, v132
	v_fmac_f32_e32 v141, 0.5, v133
	v_cvt_pk_bf16_f32 v132, v140, v141
	v_fmac_f32_e32 v186, 0.5, v138
	v_fmac_f32_e32 v197, 0.5, v137
	v_and_b32_e32 v137, 0xffff0000, v132
	v_fmac_f32_e32 v142, 0.5, v134
	v_fmac_f32_e32 v187, 0.5, v139
	v_cvt_pk_bf16_f32 v134, v186, v187
	v_fmac_f32_e32 v196, 0.5, v136
	v_lshlrev_b32_e32 v136, 16, v132
	v_mul_f32_e32 v186, v137, v137
	v_fmac_f32_e32 v143, 0.5, v135
	v_cvt_pk_bf16_f32 v133, v142, v143
	v_fmac_f32_e32 v186, v136, v136
	v_lshlrev_b32_e32 v138, 16, v133
	v_and_b32_e32 v139, 0xffff0000, v133
	v_fmac_f32_e32 v186, v138, v138
	v_lshlrev_b32_e32 v140, 16, v134
	v_fmac_f32_e32 v186, v139, v139
	v_and_b32_e32 v141, 0xffff0000, v134
	v_fmac_f32_e32 v186, v140, v140
	v_cvt_pk_bf16_f32 v135, v196, v197
	v_fmac_f32_e32 v186, v141, v141
	v_lshlrev_b32_e32 v142, 16, v135
	v_and_b32_e32 v143, 0xffff0000, v135
	v_fmac_f32_e32 v186, v142, v142
	s_waitcnt vmcnt(2)
	v_lshlrev_b32_e32 v136, 16, v128
	v_lshlrev_b32_e32 v187, 16, v130
	v_and_b32_e32 v188, 0xffff0000, v130
	v_lshlrev_b32_e32 v189, 16, v131
	v_and_b32_e32 v190, 0xffff0000, v131
	v_pk_add_f32 v[130:131], v[20:21], v[182:183]
	v_fmac_f32_e32 v186, v143, v143
	v_and_b32_e32 v137, 0xffff0000, v128
	v_lshlrev_b32_e32 v142, 16, v129
	v_and_b32_e32 v143, 0xffff0000, v129
	v_pk_add_f32 v[128:129], v[22:23], v[184:185]
	v_fmac_f32_e32 v136, 0.5, v130
	v_fmac_f32_e32 v137, 0.5, v131
	v_cvt_pk_bf16_f32 v136, v136, v137
	v_fmac_f32_e32 v142, 0.5, v128
	v_lshlrev_b32_e32 v128, 16, v136
	v_fmac_f32_e32 v143, 0.5, v129
	v_and_b32_e32 v129, 0xffff0000, v136
	v_fmac_f32_e32 v186, v128, v128
	v_cvt_pk_bf16_f32 v137, v142, v143
	v_fmac_f32_e32 v186, v129, v129
	v_lshlrev_b32_e32 v130, 16, v137
	v_pk_add_f32 v[140:141], v[18:19], v[180:181]
	v_pk_add_f32 v[138:139], v[16:17], v[178:179]
	v_and_b32_e32 v131, 0xffff0000, v137
	v_fmac_f32_e32 v186, v130, v130
	v_fmac_f32_e32 v187, 0.5, v138
	v_fmac_f32_e32 v188, 0.5, v139
	v_cvt_pk_bf16_f32 v138, v187, v188
	v_fmac_f32_e32 v189, 0.5, v140
	v_lshlrev_b32_e32 v140, 16, v138
	v_fmac_f32_e32 v186, v131, v131
	v_fmac_f32_e32 v190, 0.5, v141
	v_and_b32_e32 v141, 0xffff0000, v138
	v_fmac_f32_e32 v186, v140, v140
	v_cvt_pk_bf16_f32 v139, v189, v190
	v_fmac_f32_e32 v186, v141, v141
	v_lshlrev_b32_e32 v142, 16, v139
	v_and_b32_e32 v143, 0xffff0000, v139
	v_fmac_f32_e32 v186, v142, v142
	v_fmac_f32_e32 v186, v143, v143
	ds_bpermute_b32 v128, v237, v186
	v_lshl_add_u64 v[130:131], s[28:29], 0, v[176:177]
	v_lshl_add_u64 v[130:131], v[168:169], 1, v[130:131]
	global_store_dwordx4 v[130:131], v[132:135], off sc1
	global_store_dwordx4 v[130:131], v[136:139], off offset:256 sc1
	s_waitcnt lgkmcnt(0)
	v_add_f32_e32 v128, v186, v128
	ds_bpermute_b32 v129, v238, v128
	s_and_saveexec_b64 s[12:13], s[8:9]
	s_cbranch_execz .LBB0_421
	s_waitcnt lgkmcnt(0)
	v_add_f32_e32 v130, v128, v129
	v_lshl_add_u64 v[128:129], v[166:167], 2, s[6:7]
	global_atomic_add_f32 v[128:129], v130, off offset:576

; DI unsigned cvt_pk(float lo, float hi) { unsigned r; asm("v_cvt_pk_bf16_f32 %0, %1, %2" : "=v"(r) : "v"(lo), "v"(hi)); return r; }
;     __device__ __forceinline__ void operator()(const f32x4 (&acc)[2][2][4][2], const Unit& u, int wr, int wc, int fr, int fq) const {
;     ...
;                 for (int mm = 0; mm < 2; ++mm) {
;                     const int m = mp * 2 + mm;
;                     const int row = row0 + ai * HALF + m * 16;
;                     float s = 0.f;
; #pragma unroll
;                     for (int bj = 0; bj < 2; ++bj) {
;                         u32x4* px = (u32x4*)(X + (size_t)row * DM + col0 + bj * HALF);
;                         float xo[8]; unpack8(xin[mm][bj], xo);
;                         const f32x4 a0 = acc[ai][bj][m][0] + pv[mm][bj][0], a1 = acc[ai][bj][m][1] + pv[mm][bj][1];
;                         u32x4 w;
;                         w.x = cvt_pk(xo[0] + scale * a0[0], xo[1] + scale * a0[1]); w.y = cvt_pk(xo[2] + scale * a0[2], xo[3] + scale * a0[3]);
;                         w.z = cvt_pk(xo[4] + scale * a1[0], xo[5] + scale * a1[1]); w.w = cvt_pk(xo[6] + scale * a1[2], xo[7] + scale * a1[3]);
;                         *px = w;
;                         float xn[8]; unpack8(w, xn);
; #pragma unroll
;                         for (int j = 0; j < 8; ++j) s += xn[j] * xn[j];
;                     }
;                     s += __shfl_xor(s, 16); s += __shfl_xor(s, 32);
;                     if (fq == 0) unsafeAtomicAdd(ssn + row, s);
.LBB0_423:
	s_or_b64 exec, exec, s[12:13]
	s_waitcnt vmcnt(3)
	v_lshlrev_b32_e32 v208, 16, v140
	v_and_b32_e32 v209, 0xffff0000, v140
	v_lshlrev_b32_e32 v210, 16, v141
	v_and_b32_e32 v211, 0xffff0000, v141
	v_and_b32_e32 v245, 0xffff0000, v143
	v_pk_add_f32 v[140:141], v[44:45], v[204:205]
	v_pk_add_f32 v[170:171], v[42:43], v[202:203]
	v_lshlrev_b32_e32 v244, 16, v143
	v_fmac_f32_e32 v208, 0.5, v140
	v_fmac_f32_e32 v209, 0.5, v141
	v_cvt_pk_bf16_f32 v140, v208, v209
	v_fmac_f32_e32 v245, 0.5, v171
	v_and_b32_e32 v171, 0xffff0000, v140
	v_lshlrev_b32_e32 v214, 16, v142
	v_and_b32_e32 v215, 0xffff0000, v142
	v_pk_add_f32 v[142:143], v[46:47], v[206:207]
	v_pk_add_f32 v[200:201], v[40:41], v[200:201]
	v_fmac_f32_e32 v244, 0.5, v170
	v_lshlrev_b32_e32 v170, 16, v140
	v_mul_f32_e32 v206, v171, v171
	v_fmac_f32_e32 v210, 0.5, v142
	v_fmac_f32_e32 v211, 0.5, v143
	v_cvt_pk_bf16_f32 v141, v210, v211
	v_fmac_f32_e32 v214, 0.5, v200
	v_lshlrev_b32_e32 v200, 16, v141
	v_fmac_f32_e32 v206, v170, v170
	v_fmac_f32_e32 v215, 0.5, v201
	v_and_b32_e32 v201, 0xffff0000, v141
	v_fmac_f32_e32 v206, v200, v200
	v_cvt_pk_bf16_f32 v142, v214, v215
	v_fmac_f32_e32 v206, v201, v201
	v_lshlrev_b32_e32 v202, 16, v142
	v_and_b32_e32 v203, 0xffff0000, v142
	v_fmac_f32_e32 v206, v202, v202
	v_cvt_pk_bf16_f32 v143, v244, v245
	v_fmac_f32_e32 v206, v203, v203
	v_lshlrev_b32_e32 v204, 16, v143
	v_and_b32_e32 v205, 0xffff0000, v143
	v_fmac_f32_e32 v206, v204, v204
	v_fmac_f32_e32 v206, v205, v205
	s_waitcnt vmcnt(2)
	v_lshlrev_b32_e32 v200, 16, v136
	v_and_b32_e32 v201, 0xffff0000, v136
	v_lshlrev_b32_e32 v202, 16, v137
	v_and_b32_e32 v203, 0xffff0000, v137
	v_lshlrev_b32_e32 v204, 16, v138
	v_and_b32_e32 v205, 0xffff0000, v138
	v_lshlrev_b32_e32 v207, 16, v139
	v_and_b32_e32 v208, 0xffff0000, v139
	v_pk_add_f32 v[136:137], v[14:15], v[198:199]
	v_pk_add_f32 v[138:139], v[12:13], v[196:197]
	v_pk_add_f32 v[170:171], v[10:11], v[194:195]
	v_pk_add_f32 v[194:195], v[8:9], v[192:193]
	v_fmac_f32_e32 v200, 0.5, v138
	v_fmac_f32_e32 v201, 0.5, v139
	v_cvt_pk_bf16_f32 v192, v200, v201
	v_fmac_f32_e32 v202, 0.5, v136
	v_lshlrev_b32_e32 v136, 16, v192
	v_fmac_f32_e32 v203, 0.5, v137
	v_and_b32_e32 v137, 0xffff0000, v192
	v_fmac_f32_e32 v206, v136, v136
	v_cvt_pk_bf16_f32 v193, v202, v203
	v_fmac_f32_e32 v206, v137, v137
	v_lshlrev_b32_e32 v138, 16, v193
	v_and_b32_e32 v139, 0xffff0000, v193
	v_fmac_f32_e32 v206, v138, v138
	v_fmac_f32_e32 v204, 0.5, v194
	v_fmac_f32_e32 v205, 0.5, v195
	v_cvt_pk_bf16_f32 v194, v204, v205
	v_fmac_f32_e32 v207, 0.5, v170
	v_lshlrev_b32_e32 v170, 16, v194
	v_fmac_f32_e32 v206, v139, v139
	v_fmac_f32_e32 v208, 0.5, v171
	v_and_b32_e32 v171, 0xffff0000, v194
	v_fmac_f32_e32 v206, v170, v170
	v_cvt_pk_bf16_f32 v195, v207, v208
	v_fmac_f32_e32 v206, v171, v171
	v_lshlrev_b32_e32 v196, 16, v195
	v_and_b32_e32 v197, 0xffff0000, v195
	v_fmac_f32_e32 v206, v196, v196
	v_fmac_f32_e32 v206, v197, v197
	ds_bpermute_b32 v136, v237, v206
	v_lshl_add_u64 v[138:139], s[28:29], 0, v[182:183]
	v_lshl_add_u64 v[138:139], v[168:169], 1, v[138:139]
	global_store_dwordx4 v[138:139], v[140:143], off sc1
	global_store_dwordx4 v[138:139], v[192:195], off offset:256 sc1
	s_waitcnt lgkmcnt(0)
	v_add_f32_e32 v136, v206, v136
	ds_bpermute_b32 v137, v238, v136
	s_and_saveexec_b64 s[12:13], s[8:9]
	s_cbranch_execz .LBB0_425
	s_waitcnt lgkmcnt(0)
	v_add_f32_e32 v138, v136, v137
	v_lshl_add_u64 v[136:137], v[166:167], 2, s[6:7]
	global_atomic_add_f32 v[136:137], v138, off offset:640
.LBB0_425:
	s_or_b64 exec, exec, s[12:13]
	s_waitcnt vmcnt(3)
	v_lshlrev_b32_e32 v140, 16, v132
	v_and_b32_e32 v141, 0xffff0000, v132
	v_lshlrev_b32_e32 v142, 16, v133
	v_and_b32_e32 v143, 0xffff0000, v133
	v_lshlrev_b32_e32 v170, 16, v134
	v_and_b32_e32 v183, 0xffff0000, v135
	v_pk_add_f32 v[132:133], v[36:37], v[188:189]
	s_waitcnt lgkmcnt(0)
	v_pk_add_f32 v[136:137], v[34:35], v[186:187]
	v_pk_add_f32 v[138:139], v[32:33], v[184:185]
	v_and_b32_e32 v171, 0xffff0000, v134
	v_lshlrev_b32_e32 v182, 16, v135
	v_pk_add_f32 v[134:135], v[38:39], v[190:191]
	v_fmac_f32_e32 v140, 0.5, v132
	v_fmac_f32_e32 v141, 0.5, v133
	v_cvt_pk_bf16_f32 v132, v140, v141
	v_fmac_f32_e32 v170, 0.5, v138
	v_fmac_f32_e32 v183, 0.5, v137
	v_and_b32_e32 v137, 0xffff0000, v132
	v_fmac_f32_e32 v142, 0.5, v134
	v_fmac_f32_e32 v171, 0.5, v139
	v_cvt_pk_bf16_f32 v134, v170, v171
	v_fmac_f32_e32 v182, 0.5, v136
	v_lshlrev_b32_e32 v136, 16, v132
	v_mul_f32_e32 v170, v137, v137
	v_fmac_f32_e32 v143, 0.5, v135
	v_cvt_pk_bf16_f32 v133, v142, v143
	v_fmac_f32_e32 v170, v136, v136
	v_lshlrev_b32_e32 v138, 16, v133
	v_and_b32_e32 v139, 0xffff0000, v133
	v_fmac_f32_e32 v170, v138, v138
	v_lshlrev_b32_e32 v140, 16, v134
	v_fmac_f32_e32 v170, v139, v139
	v_and_b32_e32 v141, 0xffff0000, v134
	v_fmac_f32_e32 v170, v140, v140
	v_cvt_pk_bf16_f32 v135, v182, v183
	v_fmac_f32_e32 v170, v141, v141
	v_lshlrev_b32_e32 v142, 16, v135
	v_and_b32_e32 v143, 0xffff0000, v135
	v_fmac_f32_e32 v170, v142, v142
	s_waitcnt vmcnt(2)
	v_lshlrev_b32_e32 v136, 16, v128
	v_lshlrev_b32_e32 v171, 16, v130
	v_and_b32_e32 v182, 0xffff0000, v130
	v_lshlrev_b32_e32 v183, 16, v131
	v_and_b32_e32 v184, 0xffff0000, v131
	v_pk_add_f32 v[130:131], v[4:5], v[178:179]
	v_fmac_f32_e32 v170, v143, v143
	v_and_b32_e32 v137, 0xffff0000, v128
	v_lshlrev_b32_e32 v142, 16, v129
	v_and_b32_e32 v143, 0xffff0000, v129
	v_pk_add_f32 v[128:129], v[6:7], v[180:181]
	v_fmac_f32_e32 v136, 0.5, v130
	v_fmac_f32_e32 v137, 0.5, v131
	v_cvt_pk_bf16_f32 v136, v136, v137
	v_fmac_f32_e32 v142, 0.5, v128
	v_lshlrev_b32_e32 v128, 16, v136
	v_fmac_f32_e32 v143, 0.5, v129
	v_and_b32_e32 v129, 0xffff0000, v136
	v_fmac_f32_e32 v170, v128, v128
	v_cvt_pk_bf16_f32 v137, v142, v143
	v_fmac_f32_e32 v170, v129, v129
	v_lshlrev_b32_e32 v130, 16, v137
	v_pk_add_f32 v[140:141], v[2:3], v[176:177]
	v_pk_add_f32 v[138:139], v[0:1], v[172:173]
	v_and_b32_e32 v131, 0xffff0000, v137
	v_fmac_f32_e32 v170, v130, v130
	v_fmac_f32_e32 v171, 0.5, v138
	v_fmac_f32_e32 v182, 0.5, v139
	v_cvt_pk_bf16_f32 v138, v171, v182
	v_fmac_f32_e32 v183, 0.5, v140
	v_lshlrev_b32_e32 v140, 16, v138
	v_fmac_f32_e32 v170, v131, v131
	v_fmac_f32_e32 v184, 0.5, v141
	v_and_b32_e32 v141, 0xffff0000, v138
	v_fmac_f32_e32 v170, v140, v140
	v_cvt_pk_bf16_f32 v139, v183, v184
	v_fmac_f32_e32 v170, v141, v141
	v_lshlrev_b32_e32 v142, 16, v139
	v_and_b32_e32 v143, 0xffff0000, v139
	v_fmac_f32_e32 v170, v142, v142
	v_fmac_f32_e32 v170, v143, v143
	ds_bpermute_b32 v128, v237, v170
	v_lshl_add_u64 v[130:131], s[28:29], 0, v[174:175]
	v_lshl_add_u64 v[130:131], v[168:169], 1, v[130:131]
	global_store_dwordx4 v[130:131], v[132:135], off sc1
	global_store_dwordx4 v[130:131], v[136:139], off offset:256 sc1
	s_waitcnt lgkmcnt(0)
	v_add_f32_e32 v128, v170, v128
	ds_bpermute_b32 v129, v238, v128
	s_and_saveexec_b64 s[12:13], s[8:9]
	s_cbranch_execz .LBB0_427
	s_waitcnt lgkmcnt(0)
	v_add_f32_e32 v130, v128, v129
	v_lshl_add_u64 v[128:129], v[166:167], 2, s[6:7]
	global_atomic_add_f32 v[128:129], v130, off offset:704

; DI unsigned cvt_pk(float lo, float hi) { unsigned r; asm("v_cvt_pk_bf16_f32 %0, %1, %2" : "=v"(r) : "v"(lo), "v"(hi)); return r; }
;     __device__ __forceinline__ void operator()(const f32x4 (&acc)[2][2][4][2], const Unit& u, int wr, int wc, int fr, int fq) const {
;     ...
;                 for (int mm = 0; mm < 2; ++mm) {
;                     const int m = mp * 2 + mm;
;                     const int row = row0 + ai * HALF + m * 16;
;                     float s = 0.f;
; #pragma unroll
;                     for (int bj = 0; bj < 2; ++bj) {
;                         u32x4* px = (u32x4*)(X + (size_t)row * DM + col0 + bj * HALF);
;                         float xo[8]; unpack8(xin[mm][bj], xo);
;                         const f32x4 a0 = acc[ai][bj][m][0] + pv[mm][bj][0], a1 = acc[ai][bj][m][1] + pv[mm][bj][1];
;                         u32x4 w;
;                         w.x = cvt_pk(xo[0] + scale * a0[0], xo[1] + scale * a0[1]); w.y = cvt_pk(xo[2] + scale * a0[2], xo[3] + scale * a0[3]);
;                         w.z = cvt_pk(xo[4] + scale * a1[0], xo[5] + scale * a1[1]); w.w = cvt_pk(xo[6] + scale * a1[2], xo[7] + scale * a1[3]);
;                         *px = w;
;                         float xn[8]; unpack8(w, xn);
; #pragma unroll
;                         for (int j = 0; j < 8; ++j) s += xn[j] * xn[j];
;                     }
;                     s += __shfl_xor(s, 16); s += __shfl_xor(s, 32);
;                     if (fq == 0) unsafeAtomicAdd(ssn + row, s);
.LBB0_1161:
	s_or_b64 exec, exec, s[16:17]
	s_waitcnt vmcnt(0)
	v_lshlrev_b32_e32 v210, 16, v140
	v_and_b32_e32 v211, 0xffff0000, v140
	v_lshlrev_b32_e32 v214, 16, v141
	v_and_b32_e32 v215, 0xffff0000, v141
	v_pk_add_f32 v[140:141], v[124:125], v[206:207]
	v_lshlrev_b32_e32 v237, 16, v142
	v_and_b32_e32 v238, 0xffff0000, v142
	v_lshlrev_b32_e32 v244, 16, v143
	v_and_b32_e32 v245, 0xffff0000, v143
	v_pk_add_f32 v[142:143], v[126:127], v[208:209]
	v_add_f32_e32 v140, v140, v210
	v_add_f32_e32 v141, v141, v211
	v_pk_add_f32 v[202:203], v[120:121], v[202:203]
	v_cvt_pk_bf16_f32 v140, v140, v141
	v_add_f32_e32 v141, v142, v214
	v_add_f32_e32 v142, v143, v215
	v_pk_add_f32 v[204:205], v[122:123], v[204:205]
	v_cvt_pk_bf16_f32 v141, v141, v142
	v_add_f32_e32 v142, v202, v237
	v_add_f32_e32 v143, v203, v238
	v_cvt_pk_bf16_f32 v142, v142, v143
	v_add_f32_e32 v143, v204, v244
	v_add_f32_e32 v202, v205, v245
	v_and_b32_e32 v203, 0xffff0000, v140
	v_cvt_pk_bf16_f32 v143, v143, v202
	v_lshlrev_b32_e32 v202, 16, v140
	v_mul_f32_e32 v203, v203, v203
	v_lshlrev_b32_e32 v204, 16, v141
	v_fmac_f32_e32 v203, v202, v202
	v_and_b32_e32 v205, 0xffff0000, v141
	v_fmac_f32_e32 v203, v204, v204
	v_lshlrev_b32_e32 v206, 16, v142
	v_fmac_f32_e32 v203, v205, v205
	v_and_b32_e32 v207, 0xffff0000, v142
	v_fmac_f32_e32 v203, v206, v206
	v_lshlrev_b32_e32 v208, 16, v143
	v_fmac_f32_e32 v203, v207, v207
	v_and_b32_e32 v209, 0xffff0000, v143
	v_fmac_f32_e32 v203, v208, v208
	v_lshlrev_b32_e32 v202, 16, v136
	v_and_b32_e32 v204, 0xffff0000, v136
	v_lshlrev_b32_e32 v205, 16, v137
	v_and_b32_e32 v206, 0xffff0000, v137
	v_pk_add_f32 v[136:137], v[94:95], v[200:201]
	v_fmac_f32_e32 v203, v209, v209
	v_lshlrev_b32_e32 v207, 16, v138
	v_and_b32_e32 v208, 0xffff0000, v138
	v_lshlrev_b32_e32 v209, 16, v139
	v_and_b32_e32 v210, 0xffff0000, v139
	v_pk_add_f32 v[138:139], v[92:93], v[198:199]
	v_pk_add_f32 v[198:199], v[90:91], v[196:197]
	v_pk_add_f32 v[196:197], v[88:89], v[194:195]
	v_add_f32_e32 v136, v136, v205
	v_add_f32_e32 v137, v137, v206
	v_cvt_pk_bf16_f32 v195, v136, v137
	v_add_f32_e32 v136, v196, v207
	v_add_f32_e32 v137, v197, v208
	v_cvt_pk_bf16_f32 v196, v136, v137
	v_add_f32_e32 v136, v198, v209
	v_add_f32_e32 v138, v138, v202
	v_add_f32_e32 v139, v139, v204
	v_cvt_pk_bf16_f32 v194, v138, v139
	v_add_f32_e32 v137, v199, v210
	v_cvt_pk_bf16_f32 v197, v136, v137
	v_lshlrev_b32_e32 v136, 16, v194
	v_and_b32_e32 v137, 0xffff0000, v194
	v_fmac_f32_e32 v203, v136, v136
	v_lshlrev_b32_e32 v138, 16, v195
	v_fmac_f32_e32 v203, v137, v137
	v_and_b32_e32 v139, 0xffff0000, v195
	v_fmac_f32_e32 v203, v138, v138
	v_lshlrev_b32_e32 v198, 16, v196
	v_fmac_f32_e32 v203, v139, v139
	v_and_b32_e32 v137, 64, v221
	v_and_b32_e32 v199, 0xffff0000, v196
	v_fmac_f32_e32 v203, v198, v198
	v_xor_b32_e32 v136, 16, v221
	v_add_u32_e32 v137, 64, v137
	v_lshlrev_b32_e32 v200, 16, v197
	v_fmac_f32_e32 v203, v199, v199
	v_cmp_lt_i32_e64 s[16:17], v136, v137
	v_and_b32_e32 v201, 0xffff0000, v197
	v_fmac_f32_e32 v203, v200, v200
	v_cndmask_b32_e64 v136, v221, v136, s[16:17]
	v_fmac_f32_e32 v203, v201, v201
	v_lshlrev_b32_e32 v237, 2, v136
	ds_bpermute_b32 v136, v237, v203
	v_xor_b32_e32 v138, 32, v221
	v_cmp_lt_i32_e64 s[16:17], v138, v137
	s_waitcnt lgkmcnt(0)
	v_add_f32_e32 v136, v203, v136
	v_cndmask_b32_e64 v137, v221, v138, s[16:17]
	v_lshlrev_b32_e32 v238, 2, v137
	ds_bpermute_b32 v137, v238, v136
	v_lshl_add_u64 v[138:139], s[36:37], 0, v[174:175]
	v_lshl_add_u64 v[138:139], v[168:169], 1, v[138:139]
	global_store_dwordx4 v[138:139], v[140:143], off sc1
	global_store_dwordx4 v[138:139], v[194:197], off offset:256 sc1
	s_and_saveexec_b64 s[16:17], s[12:13]
	s_cbranch_execz .LBB0_1163
	s_waitcnt lgkmcnt(0)
	v_add_f32_e32 v138, v136, v137
	v_lshl_add_u64 v[136:137], v[166:167], 2, s[4:5]
	global_atomic_add_f32 v[136:137], v138, off
; DI unsigned cvt_pk(float lo, float hi) { unsigned r; asm("v_cvt_pk_bf16_f32 %0, %1, %2" : "=v"(r) : "v"(lo), "v"(hi)); return r; }
;     __device__ __forceinline__ void operator()(const f32x4 (&acc)[2][2][4][2], const Unit& u, int wr, int wc, int fr, int fq) const {
;     ...
;                 for (int mm = 0; mm < 2; ++mm) {
;                     const int m = mp * 2 + mm;
;                     const int row = row0 + ai * HALF + m * 16;
;                     float s = 0.f;
; #pragma unroll
;                     for (int bj = 0; bj < 2; ++bj) {
;                         u32x4* px = (u32x4*)(X + (size_t)row * DM + col0 + bj * HALF);
;                         float xo[8]; unpack8(xin[mm][bj], xo);
;                         const f32x4 a0 = acc[ai][bj][m][0] + pv[mm][bj][0], a1 = acc[ai][bj][m][1] + pv[mm][bj][1];
;                         u32x4 w;
;                         w.x = cvt_pk(xo[0] + scale * a0[0], xo[1] + scale * a0[1]); w.y = cvt_pk(xo[2] + scale * a0[2], xo[3] + scale * a0[3]);
;                         w.z = cvt_pk(xo[4] + scale * a1[0], xo[5] + scale * a1[1]); w.w = cvt_pk(xo[6] + scale * a1[2], xo[7] + scale * a1[3]);
;                         *px = w;
;                         float xn[8]; unpack8(w, xn);
; #pragma unroll
;                         for (int j = 0; j < 8; ++j) s += xn[j] * xn[j];
;                     }
;                     s += __shfl_xor(s, 16); s += __shfl_xor(s, 32);
;                     if (fq == 0) unsafeAtomicAdd(ssn + row, s);
.LBB0_1163:
	s_or_b64 exec, exec, s[16:17]
	v_lshlrev_b32_e32 v140, 16, v132
	v_and_b32_e32 v141, 0xffff0000, v132
	v_lshlrev_b32_e32 v142, 16, v133
	v_and_b32_e32 v143, 0xffff0000, v133
	v_pk_add_f32 v[132:133], v[116:117], v[190:191]
	v_lshlrev_b32_e32 v194, 16, v134
	v_and_b32_e32 v195, 0xffff0000, v134
	v_lshlrev_b32_e32 v196, 16, v135
	v_and_b32_e32 v197, 0xffff0000, v135
	v_pk_add_f32 v[134:135], v[118:119], v[192:193]
	v_add_f32_e32 v132, v132, v140
	v_add_f32_e32 v133, v133, v141
	v_pk_add_f32 v[138:139], v[112:113], v[186:187]
	v_cvt_pk_bf16_f32 v132, v132, v133
	v_add_f32_e32 v133, v134, v142
	v_add_f32_e32 v134, v135, v143
	s_waitcnt lgkmcnt(0)
	v_pk_add_f32 v[136:137], v[114:115], v[188:189]
	v_cvt_pk_bf16_f32 v133, v133, v134
	v_add_f32_e32 v134, v138, v194
	v_add_f32_e32 v135, v139, v195
	v_cvt_pk_bf16_f32 v134, v134, v135
	v_add_f32_e32 v135, v136, v196
	v_add_f32_e32 v136, v137, v197
	v_and_b32_e32 v137, 0xffff0000, v132
	v_cvt_pk_bf16_f32 v135, v135, v136
	v_lshlrev_b32_e32 v136, 16, v132
	v_mul_f32_e32 v186, v137, v137
	v_lshlrev_b32_e32 v138, 16, v133
	v_fmac_f32_e32 v186, v136, v136
	v_and_b32_e32 v139, 0xffff0000, v133
	v_fmac_f32_e32 v186, v138, v138
	v_lshlrev_b32_e32 v140, 16, v134
	v_fmac_f32_e32 v186, v139, v139
	v_and_b32_e32 v141, 0xffff0000, v134
	v_fmac_f32_e32 v186, v140, v140
	v_lshlrev_b32_e32 v142, 16, v135
	v_fmac_f32_e32 v186, v141, v141
	v_and_b32_e32 v143, 0xffff0000, v135
	v_fmac_f32_e32 v186, v142, v142
	v_fmac_f32_e32 v186, v143, v143
	v_lshlrev_b32_e32 v136, 16, v128
	v_and_b32_e32 v137, 0xffff0000, v128
	v_lshlrev_b32_e32 v142, 16, v129
	v_and_b32_e32 v143, 0xffff0000, v129
	v_pk_add_f32 v[128:129], v[86:87], v[184:185]
	v_lshlrev_b32_e32 v187, 16, v130
	v_and_b32_e32 v188, 0xffff0000, v130
	v_lshlrev_b32_e32 v189, 16, v131
	v_and_b32_e32 v190, 0xffff0000, v131
	v_pk_add_f32 v[130:131], v[84:85], v[182:183]
	v_pk_add_f32 v[138:139], v[80:81], v[178:179]
	v_add_f32_e32 v128, v128, v142
	v_pk_add_f32 v[140:141], v[82:83], v[180:181]
	v_add_f32_e32 v131, v131, v137
	v_add_f32_e32 v129, v129, v143
	v_cvt_pk_bf16_f32 v137, v128, v129
	v_add_f32_e32 v128, v138, v187
	v_add_f32_e32 v129, v139, v188
	v_cvt_pk_bf16_f32 v138, v128, v129
	v_add_f32_e32 v128, v140, v189
	v_add_f32_e32 v130, v130, v136
	v_cvt_pk_bf16_f32 v136, v130, v131
	v_add_f32_e32 v129, v141, v190
	v_cvt_pk_bf16_f32 v139, v128, v129
	v_lshlrev_b32_e32 v128, 16, v136
	v_and_b32_e32 v129, 0xffff0000, v136
	v_fmac_f32_e32 v186, v128, v128
	v_lshlrev_b32_e32 v130, 16, v137
	v_fmac_f32_e32 v186, v129, v129
	v_and_b32_e32 v131, 0xffff0000, v137
	v_fmac_f32_e32 v186, v130, v130
	v_lshlrev_b32_e32 v140, 16, v138
	v_fmac_f32_e32 v186, v131, v131
	v_and_b32_e32 v141, 0xffff0000, v138
	v_fmac_f32_e32 v186, v140, v140
	v_lshlrev_b32_e32 v142, 16, v139
	v_fmac_f32_e32 v186, v141, v141
	v_and_b32_e32 v143, 0xffff0000, v139
	v_fmac_f32_e32 v186, v142, v142
	v_fmac_f32_e32 v186, v143, v143
	ds_bpermute_b32 v128, v237, v186
	v_lshl_add_u64 v[130:131], s[36:37], 0, v[176:177]
	v_lshl_add_u64 v[130:131], v[168:169], 1, v[130:131]
	global_store_dwordx4 v[130:131], v[132:135], off sc1
	global_store_dwordx4 v[130:131], v[136:139], off offset:256 sc1
	s_waitcnt lgkmcnt(0)
	v_add_f32_e32 v128, v186, v128
	ds_bpermute_b32 v129, v238, v128
	s_and_saveexec_b64 s[16:17], s[12:13]
	s_cbranch_execz .LBB0_1165
	s_waitcnt lgkmcnt(0)
	v_add_f32_e32 v130, v128, v129
	v_lshl_add_u64 v[128:129], v[166:167], 2, s[4:5]
	global_atomic_add_f32 v[128:129], v130, off offset:64

; DI unsigned cvt_pk(float lo, float hi) { unsigned r; asm("v_cvt_pk_bf16_f32 %0, %1, %2" : "=v"(r) : "v"(lo), "v"(hi)); return r; }
;     __device__ __forceinline__ void operator()(const f32x4 (&acc)[2][2][4][2], const Unit& u, int wr, int wc, int fr, int fq) const {
;     ...
;                 for (int mm = 0; mm < 2; ++mm) {
;                     const int m = mp * 2 + mm;
;                     const int row = row0 + ai * HALF + m * 16;
;                     float s = 0.f;
; #pragma unroll
;                     for (int bj = 0; bj < 2; ++bj) {
;                         u32x4* px = (u32x4*)(X + (size_t)row * DM + col0 + bj * HALF);
;                         float xo[8]; unpack8(xin[mm][bj], xo);
;                         const f32x4 a0 = acc[ai][bj][m][0] + pv[mm][bj][0], a1 = acc[ai][bj][m][1] + pv[mm][bj][1];
;                         u32x4 w;
;                         w.x = cvt_pk(xo[0] + scale * a0[0], xo[1] + scale * a0[1]); w.y = cvt_pk(xo[2] + scale * a0[2], xo[3] + scale * a0[3]);
;                         w.z = cvt_pk(xo[4] + scale * a1[0], xo[5] + scale * a1[1]); w.w = cvt_pk(xo[6] + scale * a1[2], xo[7] + scale * a1[3]);
;                         *px = w;
;                         float xn[8]; unpack8(w, xn);
; #pragma unroll
;                         for (int j = 0; j < 8; ++j) s += xn[j] * xn[j];
;                     }
;                     s += __shfl_xor(s, 16); s += __shfl_xor(s, 32);
;                     if (fq == 0) unsafeAtomicAdd(ssn + row, s);
.LBB0_1167:
	s_or_b64 exec, exec, s[16:17]
	s_waitcnt vmcnt(3)
	v_lshlrev_b32_e32 v214, 16, v140
	v_and_b32_e32 v215, 0xffff0000, v140
	v_lshlrev_b32_e32 v244, 16, v141
	v_and_b32_e32 v245, 0xffff0000, v141
	v_pk_add_f32 v[140:141], v[108:109], v[208:209]
	v_lshlrev_b32_e32 v246, 16, v142
	v_and_b32_e32 v247, 0xffff0000, v142
	v_lshlrev_b32_e32 v248, 16, v143
	v_and_b32_e32 v249, 0xffff0000, v143
	v_pk_add_f32 v[142:143], v[110:111], v[210:211]
	v_add_f32_e32 v140, v140, v214
	v_add_f32_e32 v141, v141, v215
	v_pk_add_f32 v[204:205], v[104:105], v[204:205]
	v_cvt_pk_bf16_f32 v140, v140, v141
	v_add_f32_e32 v141, v142, v244
	v_add_f32_e32 v142, v143, v245
	v_pk_add_f32 v[206:207], v[106:107], v[206:207]
	v_cvt_pk_bf16_f32 v141, v141, v142
	v_add_f32_e32 v142, v204, v246
	v_add_f32_e32 v143, v205, v247
	v_cvt_pk_bf16_f32 v142, v142, v143
	v_add_f32_e32 v143, v206, v248
	v_add_f32_e32 v204, v207, v249
	v_and_b32_e32 v205, 0xffff0000, v140
	v_cvt_pk_bf16_f32 v143, v143, v204
	v_lshlrev_b32_e32 v204, 16, v140
	v_mul_f32_e32 v205, v205, v205
	v_lshlrev_b32_e32 v206, 16, v141
	v_fmac_f32_e32 v205, v204, v204
	v_and_b32_e32 v207, 0xffff0000, v141
	v_fmac_f32_e32 v205, v206, v206
	v_lshlrev_b32_e32 v208, 16, v142
	v_fmac_f32_e32 v205, v207, v207
	v_and_b32_e32 v209, 0xffff0000, v142
	v_fmac_f32_e32 v205, v208, v208
	v_lshlrev_b32_e32 v210, 16, v143
	v_fmac_f32_e32 v205, v209, v209
	v_and_b32_e32 v211, 0xffff0000, v143
	v_fmac_f32_e32 v205, v210, v210
	s_waitcnt vmcnt(2)
	v_lshlrev_b32_e32 v204, 16, v136
	v_and_b32_e32 v206, 0xffff0000, v136
	v_lshlrev_b32_e32 v207, 16, v137
	v_and_b32_e32 v208, 0xffff0000, v137
	v_pk_add_f32 v[136:137], v[78:79], v[202:203]
	v_fmac_f32_e32 v205, v211, v211
	v_lshlrev_b32_e32 v209, 16, v138
	v_and_b32_e32 v210, 0xffff0000, v138
	v_lshlrev_b32_e32 v211, 16, v139
	v_and_b32_e32 v214, 0xffff0000, v139
	v_pk_add_f32 v[138:139], v[76:77], v[200:201]
	v_pk_add_f32 v[200:201], v[74:75], v[198:199]
	v_pk_add_f32 v[198:199], v[72:73], v[196:197]
	v_add_f32_e32 v136, v136, v207
	v_add_f32_e32 v137, v137, v208
	v_cvt_pk_bf16_f32 v197, v136, v137
	v_add_f32_e32 v136, v198, v209
	v_add_f32_e32 v137, v199, v210
	v_cvt_pk_bf16_f32 v198, v136, v137
	v_add_f32_e32 v136, v200, v211
	v_add_f32_e32 v138, v138, v204
	v_add_f32_e32 v139, v139, v206
	v_cvt_pk_bf16_f32 v196, v138, v139
	v_add_f32_e32 v137, v201, v214
	v_cvt_pk_bf16_f32 v199, v136, v137
	v_lshlrev_b32_e32 v136, 16, v196
	v_and_b32_e32 v137, 0xffff0000, v196
	v_fmac_f32_e32 v205, v136, v136
	v_lshlrev_b32_e32 v138, 16, v197
	v_fmac_f32_e32 v205, v137, v137
	v_and_b32_e32 v139, 0xffff0000, v197
	v_fmac_f32_e32 v205, v138, v138
	v_lshlrev_b32_e32 v200, 16, v198
	v_fmac_f32_e32 v205, v139, v139
	v_and_b32_e32 v201, 0xffff0000, v198
	v_fmac_f32_e32 v205, v200, v200
	v_lshlrev_b32_e32 v202, 16, v199
	v_fmac_f32_e32 v205, v201, v201
	v_and_b32_e32 v203, 0xffff0000, v199
	v_fmac_f32_e32 v205, v202, v202
	v_fmac_f32_e32 v205, v203, v203
	ds_bpermute_b32 v136, v237, v205
	v_lshl_add_u64 v[138:139], s[36:37], 0, v[186:187]
	v_lshl_add_u64 v[138:139], v[168:169], 1, v[138:139]
	global_store_dwordx4 v[138:139], v[140:143], off sc1
	global_store_dwordx4 v[138:139], v[196:199], off offset:256 sc1
	s_waitcnt lgkmcnt(0)
	v_add_f32_e32 v136, v205, v136
	ds_bpermute_b32 v137, v238, v136
	s_and_saveexec_b64 s[16:17], s[12:13]
	s_cbranch_execz .LBB0_1169
	s_waitcnt lgkmcnt(0)
	v_add_f32_e32 v138, v136, v137
	v_lshl_add_u64 v[136:137], v[166:167], 2, s[4:5]
	global_atomic_add_f32 v[136:137], v138, off offset:128
; DI unsigned cvt_pk(float lo, float hi) { unsigned r; asm("v_cvt_pk_bf16_f32 %0, %1, %2" : "=v"(r) : "v"(lo), "v"(hi)); return r; }
;     __device__ __forceinline__ void operator()(const f32x4 (&acc)[2][2][4][2], const Unit& u, int wr, int wc, int fr, int fq) const {
;     ...
;                 for (int mm = 0; mm < 2; ++mm) {
;                     const int m = mp * 2 + mm;
;                     const int row = row0 + ai * HALF + m * 16;
;                     float s = 0.f;
; #pragma unroll
;                     for (int bj = 0; bj < 2; ++bj) {
;                         u32x4* px = (u32x4*)(X + (size_t)row * DM + col0 + bj * HALF);
;                         float xo[8]; unpack8(xin[mm][bj], xo);
;                         const f32x4 a0 = acc[ai][bj][m][0] + pv[mm][bj][0], a1 = acc[ai][bj][m][1] + pv[mm][bj][1];
;                         u32x4 w;
;                         w.x = cvt_pk(xo[0] + scale * a0[0], xo[1] + scale * a0[1]); w.y = cvt_pk(xo[2] + scale * a0[2], xo[3] + scale * a0[3]);
;                         w.z = cvt_pk(xo[4] + scale * a1[0], xo[5] + scale * a1[1]); w.w = cvt_pk(xo[6] + scale * a1[2], xo[7] + scale * a1[3]);
;                         *px = w;
;                         float xn[8]; unpack8(w, xn);
; #pragma unroll
;                         for (int j = 0; j < 8; ++j) s += xn[j] * xn[j];
;                     }
;                     s += __shfl_xor(s, 16); s += __shfl_xor(s, 32);
;                     if (fq == 0) unsafeAtomicAdd(ssn + row, s);
.LBB0_1169:
	s_or_b64 exec, exec, s[16:17]
	s_waitcnt vmcnt(3)
	v_lshlrev_b32_e32 v140, 16, v132
	v_and_b32_e32 v141, 0xffff0000, v132
	v_lshlrev_b32_e32 v142, 16, v133
	v_and_b32_e32 v143, 0xffff0000, v133
	v_pk_add_f32 v[132:133], v[100:101], v[192:193]
	v_lshlrev_b32_e32 v186, 16, v134
	v_and_b32_e32 v187, 0xffff0000, v134
	v_lshlrev_b32_e32 v196, 16, v135
	v_and_b32_e32 v197, 0xffff0000, v135
	v_pk_add_f32 v[134:135], v[102:103], v[194:195]
	v_add_f32_e32 v132, v132, v140
	v_add_f32_e32 v133, v133, v141
	v_pk_add_f32 v[138:139], v[96:97], v[188:189]
	v_cvt_pk_bf16_f32 v132, v132, v133
	v_add_f32_e32 v133, v134, v142
	v_add_f32_e32 v134, v135, v143
	s_waitcnt lgkmcnt(0)
	v_pk_add_f32 v[136:137], v[98:99], v[190:191]
	v_cvt_pk_bf16_f32 v133, v133, v134
	v_add_f32_e32 v134, v138, v186
	v_add_f32_e32 v135, v139, v187
	v_cvt_pk_bf16_f32 v134, v134, v135
	v_add_f32_e32 v135, v136, v196
	v_add_f32_e32 v136, v137, v197
	v_and_b32_e32 v137, 0xffff0000, v132
	v_cvt_pk_bf16_f32 v135, v135, v136
	v_lshlrev_b32_e32 v136, 16, v132
	v_mul_f32_e32 v186, v137, v137
	v_lshlrev_b32_e32 v138, 16, v133
	v_fmac_f32_e32 v186, v136, v136
	v_and_b32_e32 v139, 0xffff0000, v133
	v_fmac_f32_e32 v186, v138, v138
	v_lshlrev_b32_e32 v140, 16, v134
	v_fmac_f32_e32 v186, v139, v139
	v_and_b32_e32 v141, 0xffff0000, v134
	v_fmac_f32_e32 v186, v140, v140
	v_lshlrev_b32_e32 v142, 16, v135
	v_fmac_f32_e32 v186, v141, v141
	v_and_b32_e32 v143, 0xffff0000, v135
	v_fmac_f32_e32 v186, v142, v142
	v_fmac_f32_e32 v186, v143, v143
	s_waitcnt vmcnt(2)
	v_lshlrev_b32_e32 v136, 16, v128
	v_and_b32_e32 v137, 0xffff0000, v128
	v_lshlrev_b32_e32 v142, 16, v129
	v_and_b32_e32 v143, 0xffff0000, v129
	v_pk_add_f32 v[128:129], v[70:71], v[184:185]
	v_lshlrev_b32_e32 v187, 16, v130
	v_and_b32_e32 v188, 0xffff0000, v130
	v_lshlrev_b32_e32 v189, 16, v131
	v_and_b32_e32 v190, 0xffff0000, v131
	v_pk_add_f32 v[130:131], v[68:69], v[182:183]
	v_pk_add_f32 v[138:139], v[64:65], v[178:179]
	v_add_f32_e32 v128, v128, v142
	v_pk_add_f32 v[140:141], v[66:67], v[180:181]
	v_add_f32_e32 v131, v131, v137
	v_add_f32_e32 v129, v129, v143
	v_cvt_pk_bf16_f32 v137, v128, v129
	v_add_f32_e32 v128, v138, v187
	v_add_f32_e32 v129, v139, v188
	v_cvt_pk_bf16_f32 v138, v128, v129
	v_add_f32_e32 v128, v140, v189
	v_add_f32_e32 v130, v130, v136
	v_cvt_pk_bf16_f32 v136, v130, v131
	v_add_f32_e32 v129, v141, v190
	v_cvt_pk_bf16_f32 v139, v128, v129
	v_lshlrev_b32_e32 v128, 16, v136
	v_and_b32_e32 v129, 0xffff0000, v136
	v_fmac_f32_e32 v186, v128, v128
	v_lshlrev_b32_e32 v130, 16, v137
	v_fmac_f32_e32 v186, v129, v129
	v_and_b32_e32 v131, 0xffff0000, v137
	v_fmac_f32_e32 v186, v130, v130
	v_lshlrev_b32_e32 v140, 16, v138
	v_fmac_f32_e32 v186, v131, v131
	v_and_b32_e32 v141, 0xffff0000, v138
	v_fmac_f32_e32 v186, v140, v140
	v_lshlrev_b32_e32 v142, 16, v139
	v_fmac_f32_e32 v186, v141, v141
	v_and_b32_e32 v143, 0xffff0000, v139
	v_fmac_f32_e32 v186, v142, v142
	v_fmac_f32_e32 v186, v143, v143
	ds_bpermute_b32 v128, v237, v186
	v_lshl_add_u64 v[130:131], s[36:37], 0, v[176:177]
	v_lshl_add_u64 v[130:131], v[168:169], 1, v[130:131]
	global_store_dwordx4 v[130:131], v[132:135], off sc1
	global_store_dwordx4 v[130:131], v[136:139], off offset:256 sc1
	s_waitcnt lgkmcnt(0)
	v_add_f32_e32 v128, v186, v128
	ds_bpermute_b32 v129, v238, v128
	s_and_saveexec_b64 s[16:17], s[12:13]
	s_cbranch_execz .LBB0_1171
	s_waitcnt lgkmcnt(0)
	v_add_f32_e32 v130, v128, v129
	v_lshl_add_u64 v[128:129], v[166:167], 2, s[4:5]
	global_atomic_add_f32 v[128:129], v130, off offset:192

; DI unsigned cvt_pk(float lo, float hi) { unsigned r; asm("v_cvt_pk_bf16_f32 %0, %1, %2" : "=v"(r) : "v"(lo), "v"(hi)); return r; }
;     __device__ __forceinline__ void operator()(const f32x4 (&acc)[2][2][4][2], const Unit& u, int wr, int wc, int fr, int fq) const {
;     ...
;                 for (int mm = 0; mm < 2; ++mm) {
;                     const int m = mp * 2 + mm;
;                     const int row = row0 + ai * HALF + m * 16;
;                     float s = 0.f;
; #pragma unroll
;                     for (int bj = 0; bj < 2; ++bj) {
;                         u32x4* px = (u32x4*)(X + (size_t)row * DM + col0 + bj * HALF);
;                         float xo[8]; unpack8(xin[mm][bj], xo);
;                         const f32x4 a0 = acc[ai][bj][m][0] + pv[mm][bj][0], a1 = acc[ai][bj][m][1] + pv[mm][bj][1];
;                         u32x4 w;
;                         w.x = cvt_pk(xo[0] + scale * a0[0], xo[1] + scale * a0[1]); w.y = cvt_pk(xo[2] + scale * a0[2], xo[3] + scale * a0[3]);
;                         w.z = cvt_pk(xo[4] + scale * a1[0], xo[5] + scale * a1[1]); w.w = cvt_pk(xo[6] + scale * a1[2], xo[7] + scale * a1[3]);
;                         *px = w;
;                         float xn[8]; unpack8(w, xn);
; #pragma unroll
;                         for (int j = 0; j < 8; ++j) s += xn[j] * xn[j];
;                     }
;                     s += __shfl_xor(s, 16); s += __shfl_xor(s, 32);
;                     if (fq == 0) unsafeAtomicAdd(ssn + row, s);
.LBB0_1173:
	s_or_b64 exec, exec, s[16:17]
	s_waitcnt vmcnt(3)
	v_lshlrev_b32_e32 v214, 16, v140
	v_and_b32_e32 v215, 0xffff0000, v140
	v_lshlrev_b32_e32 v244, 16, v141
	v_and_b32_e32 v245, 0xffff0000, v141
	v_pk_add_f32 v[140:141], v[60:61], v[208:209]
	v_lshlrev_b32_e32 v246, 16, v142
	v_and_b32_e32 v247, 0xffff0000, v142
	v_lshlrev_b32_e32 v248, 16, v143
	v_and_b32_e32 v249, 0xffff0000, v143
	v_pk_add_f32 v[142:143], v[62:63], v[210:211]
	v_add_f32_e32 v140, v140, v214
	v_add_f32_e32 v141, v141, v215
	v_pk_add_f32 v[204:205], v[56:57], v[204:205]
	v_cvt_pk_bf16_f32 v140, v140, v141
	v_add_f32_e32 v141, v142, v244
	v_add_f32_e32 v142, v143, v245
	v_pk_add_f32 v[206:207], v[58:59], v[206:207]
	v_cvt_pk_bf16_f32 v141, v141, v142
	v_add_f32_e32 v142, v204, v246
	v_add_f32_e32 v143, v205, v247
	v_cvt_pk_bf16_f32 v142, v142, v143
	v_add_f32_e32 v143, v206, v248
	v_add_f32_e32 v204, v207, v249
	v_and_b32_e32 v205, 0xffff0000, v140
	v_cvt_pk_bf16_f32 v143, v143, v204
	v_lshlrev_b32_e32 v204, 16, v140
	v_mul_f32_e32 v205, v205, v205
	v_lshlrev_b32_e32 v206, 16, v141
	v_fmac_f32_e32 v205, v204, v204
	v_and_b32_e32 v207, 0xffff0000, v141
	v_fmac_f32_e32 v205, v206, v206
	v_lshlrev_b32_e32 v208, 16, v142
	v_fmac_f32_e32 v205, v207, v207
	v_and_b32_e32 v209, 0xffff0000, v142
	v_fmac_f32_e32 v205, v208, v208
	v_lshlrev_b32_e32 v210, 16, v143
	v_fmac_f32_e32 v205, v209, v209
	v_and_b32_e32 v211, 0xffff0000, v143
	v_fmac_f32_e32 v205, v210, v210
	s_waitcnt vmcnt(2)
	v_lshlrev_b32_e32 v204, 16, v136
	v_and_b32_e32 v206, 0xffff0000, v136
	v_lshlrev_b32_e32 v207, 16, v137
	v_and_b32_e32 v208, 0xffff0000, v137
	v_pk_add_f32 v[136:137], v[30:31], v[202:203]
	v_fmac_f32_e32 v205, v211, v211
	v_lshlrev_b32_e32 v209, 16, v138
	v_and_b32_e32 v210, 0xffff0000, v138
	v_lshlrev_b32_e32 v211, 16, v139
	v_and_b32_e32 v214, 0xffff0000, v139
	v_pk_add_f32 v[138:139], v[28:29], v[200:201]
	v_pk_add_f32 v[200:201], v[26:27], v[198:199]
	v_pk_add_f32 v[198:199], v[24:25], v[196:197]
	v_add_f32_e32 v136, v136, v207
	v_add_f32_e32 v137, v137, v208
	v_cvt_pk_bf16_f32 v197, v136, v137
	v_add_f32_e32 v136, v198, v209
	v_add_f32_e32 v137, v199, v210
	v_cvt_pk_bf16_f32 v198, v136, v137
	v_add_f32_e32 v136, v200, v211
	v_add_f32_e32 v138, v138, v204
	v_add_f32_e32 v139, v139, v206
	v_cvt_pk_bf16_f32 v196, v138, v139
	v_add_f32_e32 v137, v201, v214
	v_cvt_pk_bf16_f32 v199, v136, v137
	v_lshlrev_b32_e32 v136, 16, v196
	v_and_b32_e32 v137, 0xffff0000, v196
	v_fmac_f32_e32 v205, v136, v136
	v_lshlrev_b32_e32 v138, 16, v197
	v_fmac_f32_e32 v205, v137, v137
	v_and_b32_e32 v139, 0xffff0000, v197
	v_fmac_f32_e32 v205, v138, v138
	v_lshlrev_b32_e32 v200, 16, v198
	v_fmac_f32_e32 v205, v139, v139
	v_and_b32_e32 v201, 0xffff0000, v198
	v_fmac_f32_e32 v205, v200, v200
	v_lshlrev_b32_e32 v202, 16, v199
	v_fmac_f32_e32 v205, v201, v201
	v_and_b32_e32 v203, 0xffff0000, v199
	v_fmac_f32_e32 v205, v202, v202
	v_fmac_f32_e32 v205, v203, v203
	ds_bpermute_b32 v136, v237, v205
	v_lshl_add_u64 v[138:139], s[36:37], 0, v[186:187]
	v_lshl_add_u64 v[138:139], v[168:169], 1, v[138:139]
	global_store_dwordx4 v[138:139], v[140:143], off sc1
	global_store_dwordx4 v[138:139], v[196:199], off offset:256 sc1
	s_waitcnt lgkmcnt(0)
	v_add_f32_e32 v136, v205, v136
	ds_bpermute_b32 v137, v238, v136
	s_and_saveexec_b64 s[16:17], s[12:13]
	s_cbranch_execz .LBB0_1175
	s_waitcnt lgkmcnt(0)
	v_add_f32_e32 v138, v136, v137
	v_lshl_add_u64 v[136:137], v[166:167], 2, s[4:5]
	global_atomic_add_f32 v[136:137], v138, off offset:512
.LBB0_1175:
	s_or_b64 exec, exec, s[16:17]
	s_waitcnt vmcnt(3)
	v_lshlrev_b32_e32 v140, 16, v132
	v_and_b32_e32 v141, 0xffff0000, v132
	v_lshlrev_b32_e32 v142, 16, v133
	v_and_b32_e32 v143, 0xffff0000, v133
	v_pk_add_f32 v[132:133], v[52:53], v[192:193]
	v_lshlrev_b32_e32 v186, 16, v134
	v_and_b32_e32 v187, 0xffff0000, v134
	v_lshlrev_b32_e32 v196, 16, v135
	v_and_b32_e32 v197, 0xffff0000, v135
	v_pk_add_f32 v[134:135], v[54:55], v[194:195]
	v_add_f32_e32 v132, v132, v140
	v_add_f32_e32 v133, v133, v141
	v_pk_add_f32 v[138:139], v[48:49], v[188:189]
	v_cvt_pk_bf16_f32 v132, v132, v133
	v_add_f32_e32 v133, v134, v142
	v_add_f32_e32 v134, v135, v143
	s_waitcnt lgkmcnt(0)
	v_pk_add_f32 v[136:137], v[50:51], v[190:191]
	v_cvt_pk_bf16_f32 v133, v133, v134
	v_add_f32_e32 v134, v138, v186
	v_add_f32_e32 v135, v139, v187
	v_cvt_pk_bf16_f32 v134, v134, v135
	v_add_f32_e32 v135, v136, v196
	v_add_f32_e32 v136, v137, v197
	v_and_b32_e32 v137, 0xffff0000, v132
	v_cvt_pk_bf16_f32 v135, v135, v136
	v_lshlrev_b32_e32 v136, 16, v132
	v_mul_f32_e32 v186, v137, v137
	v_lshlrev_b32_e32 v138, 16, v133
	v_fmac_f32_e32 v186, v136, v136
	v_and_b32_e32 v139, 0xffff0000, v133
	v_fmac_f32_e32 v186, v138, v138
	v_lshlrev_b32_e32 v140, 16, v134
	v_fmac_f32_e32 v186, v139, v139
	v_and_b32_e32 v141, 0xffff0000, v134
	v_fmac_f32_e32 v186, v140, v140
	v_lshlrev_b32_e32 v142, 16, v135
	v_fmac_f32_e32 v186, v141, v141
	v_and_b32_e32 v143, 0xffff0000, v135
	v_fmac_f32_e32 v186, v142, v142
	v_fmac_f32_e32 v186, v143, v143
	s_waitcnt vmcnt(2)
	v_lshlrev_b32_e32 v136, 16, v128
	v_and_b32_e32 v137, 0xffff0000, v128
	v_lshlrev_b32_e32 v142, 16, v129
	v_and_b32_e32 v143, 0xffff0000, v129
	v_pk_add_f32 v[128:129], v[22:23], v[184:185]
	v_lshlrev_b32_e32 v187, 16, v130
	v_and_b32_e32 v188, 0xffff0000, v130
	v_lshlrev_b32_e32 v189, 16, v131
	v_and_b32_e32 v190, 0xffff0000, v131
	v_pk_add_f32 v[130:131], v[20:21], v[182:183]
	v_pk_add_f32 v[138:139], v[16:17], v[178:179]
	v_add_f32_e32 v128, v128, v142
	v_pk_add_f32 v[140:141], v[18:19], v[180:181]
	v_add_f32_e32 v131, v131, v137
	v_add_f32_e32 v129, v129, v143
	v_cvt_pk_bf16_f32 v137, v128, v129
	v_add_f32_e32 v128, v138, v187
	v_add_f32_e32 v129, v139, v188
	v_cvt_pk_bf16_f32 v138, v128, v129
	v_add_f32_e32 v128, v140, v189
	v_add_f32_e32 v130, v130, v136
	v_cvt_pk_bf16_f32 v136, v130, v131
	v_add_f32_e32 v129, v141, v190
	v_cvt_pk_bf16_f32 v139, v128, v129
	v_lshlrev_b32_e32 v128, 16, v136
	v_and_b32_e32 v129, 0xffff0000, v136
	v_fmac_f32_e32 v186, v128, v128
	v_lshlrev_b32_e32 v130, 16, v137
	v_fmac_f32_e32 v186, v129, v129
	v_and_b32_e32 v131, 0xffff0000, v137
	v_fmac_f32_e32 v186, v130, v130
	v_lshlrev_b32_e32 v140, 16, v138
	v_fmac_f32_e32 v186, v131, v131
	v_and_b32_e32 v141, 0xffff0000, v138
	v_fmac_f32_e32 v186, v140, v140
	v_lshlrev_b32_e32 v142, 16, v139
	v_fmac_f32_e32 v186, v141, v141
	v_and_b32_e32 v143, 0xffff0000, v139
	v_fmac_f32_e32 v186, v142, v142
	v_fmac_f32_e32 v186, v143, v143
	ds_bpermute_b32 v128, v237, v186
	v_lshl_add_u64 v[130:131], s[36:37], 0, v[176:177]
	v_lshl_add_u64 v[130:131], v[168:169], 1, v[130:131]
	global_store_dwordx4 v[130:131], v[132:135], off sc1
	global_store_dwordx4 v[130:131], v[136:139], off offset:256 sc1
	s_waitcnt lgkmcnt(0)
	v_add_f32_e32 v128, v186, v128
	ds_bpermute_b32 v129, v238, v128
	s_and_saveexec_b64 s[16:17], s[12:13]
	s_cbranch_execz .LBB0_1177
	s_waitcnt lgkmcnt(0)
	v_add_f32_e32 v130, v128, v129
	v_lshl_add_u64 v[128:129], v[166:167], 2, s[4:5]
	global_atomic_add_f32 v[128:129], v130, off offset:576

; DI unsigned cvt_pk(float lo, float hi) { unsigned r; asm("v_cvt_pk_bf16_f32 %0, %1, %2" : "=v"(r) : "v"(lo), "v"(hi)); return r; }
;     __device__ __forceinline__ void operator()(const f32x4 (&acc)[2][2][4][2], const Unit& u, int wr, int wc, int fr, int fq) const {
;     ...
;                 for (int mm = 0; mm < 2; ++mm) {
;                     const int m = mp * 2 + mm;
;                     const int row = row0 + ai * HALF + m * 16;
;                     float s = 0.f;
; #pragma unroll
;                     for (int bj = 0; bj < 2; ++bj) {
;                         u32x4* px = (u32x4*)(X + (size_t)row * DM + col0 + bj * HALF);
;                         float xo[8]; unpack8(xin[mm][bj], xo);
;                         const f32x4 a0 = acc[ai][bj][m][0] + pv[mm][bj][0], a1 = acc[ai][bj][m][1] + pv[mm][bj][1];
;                         u32x4 w;
;                         w.x = cvt_pk(xo[0] + scale * a0[0], xo[1] + scale * a0[1]); w.y = cvt_pk(xo[2] + scale * a0[2], xo[3] + scale * a0[3]);
;                         w.z = cvt_pk(xo[4] + scale * a1[0], xo[5] + scale * a1[1]); w.w = cvt_pk(xo[6] + scale * a1[2], xo[7] + scale * a1[3]);
;                         *px = w;
;                         float xn[8]; unpack8(w, xn);
; #pragma unroll
;                         for (int j = 0; j < 8; ++j) s += xn[j] * xn[j];
;                     }
;                     s += __shfl_xor(s, 16); s += __shfl_xor(s, 32);
;                     if (fq == 0) unsafeAtomicAdd(ssn + row, s);
.LBB0_1179:
	s_or_b64 exec, exec, s[16:17]
	s_waitcnt vmcnt(3)
	v_lshlrev_b32_e32 v208, 16, v140
	v_and_b32_e32 v209, 0xffff0000, v140
	v_lshlrev_b32_e32 v210, 16, v141
	v_and_b32_e32 v211, 0xffff0000, v141
	v_pk_add_f32 v[140:141], v[44:45], v[204:205]
	v_lshlrev_b32_e32 v214, 16, v142
	v_and_b32_e32 v215, 0xffff0000, v142
	v_lshlrev_b32_e32 v244, 16, v143
	v_and_b32_e32 v245, 0xffff0000, v143
	v_pk_add_f32 v[142:143], v[46:47], v[206:207]
	v_add_f32_e32 v140, v140, v208
	v_add_f32_e32 v141, v141, v209
	v_pk_add_f32 v[200:201], v[40:41], v[200:201]
	v_cvt_pk_bf16_f32 v140, v140, v141
	v_add_f32_e32 v141, v142, v210
	v_add_f32_e32 v142, v143, v211
	v_pk_add_f32 v[170:171], v[42:43], v[202:203]
	v_cvt_pk_bf16_f32 v141, v141, v142
	v_add_f32_e32 v142, v200, v214
	v_add_f32_e32 v143, v201, v215
	v_cvt_pk_bf16_f32 v142, v142, v143
	v_add_f32_e32 v143, v170, v244
	v_add_f32_e32 v170, v171, v245
	v_and_b32_e32 v171, 0xffff0000, v140
	v_cvt_pk_bf16_f32 v143, v143, v170
	v_lshlrev_b32_e32 v170, 16, v140
	v_mul_f32_e32 v206, v171, v171
	v_lshlrev_b32_e32 v200, 16, v141
	v_fmac_f32_e32 v206, v170, v170
	v_and_b32_e32 v201, 0xffff0000, v141
	v_fmac_f32_e32 v206, v200, v200
	v_lshlrev_b32_e32 v202, 16, v142
	v_fmac_f32_e32 v206, v201, v201
	v_and_b32_e32 v203, 0xffff0000, v142
	v_fmac_f32_e32 v206, v202, v202
	v_lshlrev_b32_e32 v204, 16, v143
	v_fmac_f32_e32 v206, v203, v203
	s_waitcnt vmcnt(2)
	v_lshlrev_b32_e32 v200, 16, v136
	v_and_b32_e32 v201, 0xffff0000, v136
	v_lshlrev_b32_e32 v202, 16, v137
	v_and_b32_e32 v203, 0xffff0000, v137
	v_pk_add_f32 v[136:137], v[14:15], v[198:199]
	v_and_b32_e32 v205, 0xffff0000, v143
	v_fmac_f32_e32 v206, v204, v204
	v_lshlrev_b32_e32 v204, 16, v138
	v_pk_add_f32 v[170:171], v[10:11], v[194:195]
	v_pk_add_f32 v[194:195], v[8:9], v[192:193]
	v_add_f32_e32 v136, v136, v202
	v_fmac_f32_e32 v206, v205, v205
	v_and_b32_e32 v205, 0xffff0000, v138
	v_lshlrev_b32_e32 v207, 16, v139
	v_add_f32_e32 v137, v137, v203
	v_cvt_pk_bf16_f32 v193, v136, v137
	v_add_f32_e32 v136, v194, v204
	v_and_b32_e32 v208, 0xffff0000, v139
	v_pk_add_f32 v[138:139], v[12:13], v[196:197]
	v_add_f32_e32 v137, v195, v205
	v_cvt_pk_bf16_f32 v194, v136, v137
	v_add_f32_e32 v136, v170, v207
	v_add_f32_e32 v138, v138, v200
	v_add_f32_e32 v139, v139, v201
	v_cvt_pk_bf16_f32 v192, v138, v139
	v_add_f32_e32 v137, v171, v208
	v_cvt_pk_bf16_f32 v195, v136, v137
	v_lshlrev_b32_e32 v136, 16, v192
	v_and_b32_e32 v137, 0xffff0000, v192
	v_fmac_f32_e32 v206, v136, v136
	v_lshlrev_b32_e32 v138, 16, v193
	v_fmac_f32_e32 v206, v137, v137
	v_and_b32_e32 v139, 0xffff0000, v193
	v_fmac_f32_e32 v206, v138, v138
	v_lshlrev_b32_e32 v170, 16, v194
	v_fmac_f32_e32 v206, v139, v139
	v_and_b32_e32 v171, 0xffff0000, v194
	v_fmac_f32_e32 v206, v170, v170
	v_lshlrev_b32_e32 v196, 16, v195
	v_fmac_f32_e32 v206, v171, v171
	v_and_b32_e32 v197, 0xffff0000, v195
	v_fmac_f32_e32 v206, v196, v196
	v_fmac_f32_e32 v206, v197, v197
	ds_bpermute_b32 v136, v237, v206
	v_lshl_add_u64 v[138:139], s[36:37], 0, v[182:183]
	v_lshl_add_u64 v[138:139], v[168:169], 1, v[138:139]
	global_store_dwordx4 v[138:139], v[140:143], off sc1
	global_store_dwordx4 v[138:139], v[192:195], off offset:256 sc1
	s_waitcnt lgkmcnt(0)
	v_add_f32_e32 v136, v206, v136
	ds_bpermute_b32 v137, v238, v136
	s_and_saveexec_b64 s[16:17], s[12:13]
	s_cbranch_execz .LBB0_1181
	s_waitcnt lgkmcnt(0)
	v_add_f32_e32 v138, v136, v137
	v_lshl_add_u64 v[136:137], v[166:167], 2, s[4:5]
	global_atomic_add_f32 v[136:137], v138, off offset:640
.LBB0_1181:
	s_or_b64 exec, exec, s[16:17]
	s_waitcnt vmcnt(3)
	v_lshlrev_b32_e32 v140, 16, v132
	v_and_b32_e32 v141, 0xffff0000, v132
	v_lshlrev_b32_e32 v142, 16, v133
	v_and_b32_e32 v143, 0xffff0000, v133
	v_pk_add_f32 v[132:133], v[36:37], v[188:189]
	v_lshlrev_b32_e32 v170, 16, v134
	v_and_b32_e32 v171, 0xffff0000, v134
	v_lshlrev_b32_e32 v182, 16, v135
	v_and_b32_e32 v183, 0xffff0000, v135
	v_pk_add_f32 v[134:135], v[38:39], v[190:191]
	v_add_f32_e32 v132, v132, v140
	v_add_f32_e32 v133, v133, v141
	v_pk_add_f32 v[138:139], v[32:33], v[184:185]
	v_cvt_pk_bf16_f32 v132, v132, v133
	v_add_f32_e32 v133, v134, v142
	v_add_f32_e32 v134, v135, v143
	s_waitcnt lgkmcnt(0)
	v_pk_add_f32 v[136:137], v[34:35], v[186:187]
	v_cvt_pk_bf16_f32 v133, v133, v134
	v_add_f32_e32 v134, v138, v170
	v_add_f32_e32 v135, v139, v171
	v_cvt_pk_bf16_f32 v134, v134, v135
	v_add_f32_e32 v135, v136, v182
	v_add_f32_e32 v136, v137, v183
	v_and_b32_e32 v137, 0xffff0000, v132
	v_cvt_pk_bf16_f32 v135, v135, v136
	v_lshlrev_b32_e32 v136, 16, v132
	v_mul_f32_e32 v170, v137, v137
	v_lshlrev_b32_e32 v138, 16, v133
	v_fmac_f32_e32 v170, v136, v136
	v_and_b32_e32 v139, 0xffff0000, v133
	v_fmac_f32_e32 v170, v138, v138
	v_lshlrev_b32_e32 v140, 16, v134
	v_fmac_f32_e32 v170, v139, v139
	v_and_b32_e32 v141, 0xffff0000, v134
	v_fmac_f32_e32 v170, v140, v140
	v_lshlrev_b32_e32 v142, 16, v135
	v_fmac_f32_e32 v170, v141, v141
	v_and_b32_e32 v143, 0xffff0000, v135
	v_fmac_f32_e32 v170, v142, v142
	v_fmac_f32_e32 v170, v143, v143
	s_waitcnt vmcnt(2)
	v_lshlrev_b32_e32 v136, 16, v128
	v_and_b32_e32 v137, 0xffff0000, v128
	v_lshlrev_b32_e32 v142, 16, v129
	v_and_b32_e32 v143, 0xffff0000, v129
	v_pk_add_f32 v[128:129], v[6:7], v[180:181]
	v_lshlrev_b32_e32 v171, 16, v130
	v_and_b32_e32 v182, 0xffff0000, v130
	v_lshlrev_b32_e32 v183, 16, v131
	v_and_b32_e32 v184, 0xffff0000, v131
	v_pk_add_f32 v[130:131], v[4:5], v[178:179]
	v_pk_add_f32 v[138:139], v[0:1], v[172:173]
	v_add_f32_e32 v128, v128, v142
	v_pk_add_f32 v[140:141], v[2:3], v[176:177]
	v_add_f32_e32 v131, v131, v137
	v_add_f32_e32 v129, v129, v143
	v_cvt_pk_bf16_f32 v137, v128, v129
	v_add_f32_e32 v128, v138, v171
	v_add_f32_e32 v129, v139, v182
	v_cvt_pk_bf16_f32 v138, v128, v129
	v_add_f32_e32 v128, v140, v183
	v_add_f32_e32 v130, v130, v136
	v_cvt_pk_bf16_f32 v136, v130, v131
	v_add_f32_e32 v129, v141, v184
	v_cvt_pk_bf16_f32 v139, v128, v129
	v_lshlrev_b32_e32 v128, 16, v136
	v_and_b32_e32 v129, 0xffff0000, v136
	v_fmac_f32_e32 v170, v128, v128
	v_lshlrev_b32_e32 v130, 16, v137
	v_fmac_f32_e32 v170, v129, v129
	v_and_b32_e32 v131, 0xffff0000, v137
	v_fmac_f32_e32 v170, v130, v130
	v_lshlrev_b32_e32 v140, 16, v138
	v_fmac_f32_e32 v170, v131, v131
	v_and_b32_e32 v141, 0xffff0000, v138
	v_fmac_f32_e32 v170, v140, v140
	v_lshlrev_b32_e32 v142, 16, v139
	v_fmac_f32_e32 v170, v141, v141
	v_and_b32_e32 v143, 0xffff0000, v139
	v_fmac_f32_e32 v170, v142, v142
	v_fmac_f32_e32 v170, v143, v143
	ds_bpermute_b32 v128, v237, v170
	v_lshl_add_u64 v[130:131], s[36:37], 0, v[174:175]
	v_lshl_add_u64 v[130:131], v[168:169], 1, v[130:131]
	global_store_dwordx4 v[130:131], v[132:135], off sc1
	global_store_dwordx4 v[130:131], v[136:139], off offset:256 sc1
	s_waitcnt lgkmcnt(0)
	v_add_f32_e32 v128, v170, v128
	ds_bpermute_b32 v129, v238, v128
	s_and_saveexec_b64 s[16:17], s[12:13]
	s_cbranch_execz .LBB0_1183
	s_waitcnt lgkmcnt(0)
	v_add_f32_e32 v130, v128, v129
	v_lshl_add_u64 v[128:129], v[166:167], 2, s[4:5]
	global_atomic_add_f32 v[128:129], v130, off offset:704

; DI unsigned cvt_pk(float lo, float hi) { unsigned r; asm("v_cvt_pk_bf16_f32 %0, %1, %2" : "=v"(r) : "v"(lo), "v"(hi)); return r; }
;     __device__ __forceinline__ void operator()(const f32x4 (&acc)[2][2][4][2], const Unit& u, int wr, int wc, int fr, int fq) const {
;     ...
;                 for (int mm = 0; mm < 2; ++mm) {
;                     const int m = mp * 2 + mm;
;                     const int row = row0 + ai * HALF + m * 16;
;                     float s = 0.f;
; #pragma unroll
;                     for (int bj = 0; bj < 2; ++bj) {
;                         u32x4* px = (u32x4*)(X + (size_t)row * DM + col0 + bj * HALF);
;                         float xo[8]; unpack8(xin[mm][bj], xo);
;                         const f32x4 a0 = acc[ai][bj][m][0] + pv[mm][bj][0], a1 = acc[ai][bj][m][1] + pv[mm][bj][1];
;                         u32x4 w;
;                         w.x = cvt_pk(xo[0] + scale * a0[0], xo[1] + scale * a0[1]); w.y = cvt_pk(xo[2] + scale * a0[2], xo[3] + scale * a0[3]);
;                         w.z = cvt_pk(xo[4] + scale * a1[0], xo[5] + scale * a1[1]); w.w = cvt_pk(xo[6] + scale * a1[2], xo[7] + scale * a1[3]);
;                         *px = w;
;                         float xn[8]; unpack8(w, xn);
; #pragma unroll
;                         for (int j = 0; j < 8; ++j) s += xn[j] * xn[j];
;                     }
;                     s += __shfl_xor(s, 16); s += __shfl_xor(s, 32);
;                     if (fq == 0) unsafeAtomicAdd(ssn + row, s);
.LBB0_1406:
	s_or_b64 exec, exec, s[12:13]
	s_waitcnt vmcnt(0)
	v_lshlrev_b32_e32 v210, 16, v140
	v_and_b32_e32 v211, 0xffff0000, v140
	v_lshlrev_b32_e32 v214, 16, v141
	v_and_b32_e32 v215, 0xffff0000, v141
	v_and_b32_e32 v238, 0xffff0000, v142
	v_pk_add_f32 v[140:141], v[124:125], v[206:207]
	v_pk_add_f32 v[202:203], v[120:121], v[202:203]
	v_lshlrev_b32_e32 v237, 16, v142
	v_fmac_f32_e32 v210, 0.5, v140
	v_fmac_f32_e32 v211, 0.5, v141
	v_cvt_pk_bf16_f32 v140, v210, v211
	v_fmac_f32_e32 v238, 0.5, v203
	v_and_b32_e32 v203, 0xffff0000, v140
	v_lshlrev_b32_e32 v244, 16, v143
	v_and_b32_e32 v245, 0xffff0000, v143
	v_pk_add_f32 v[142:143], v[126:127], v[208:209]
	v_pk_add_f32 v[204:205], v[122:123], v[204:205]
	v_fmac_f32_e32 v237, 0.5, v202
	v_lshlrev_b32_e32 v202, 16, v140
	v_mul_f32_e32 v203, v203, v203
	v_fmac_f32_e32 v214, 0.5, v142
	v_fmac_f32_e32 v215, 0.5, v143
	v_cvt_pk_bf16_f32 v141, v214, v215
	v_fmac_f32_e32 v244, 0.5, v204
	v_lshlrev_b32_e32 v204, 16, v141
	v_fmac_f32_e32 v203, v202, v202
	v_fmac_f32_e32 v245, 0.5, v205
	v_and_b32_e32 v205, 0xffff0000, v141
	v_fmac_f32_e32 v203, v204, v204
	v_cvt_pk_bf16_f32 v142, v237, v238
	v_fmac_f32_e32 v203, v205, v205
	v_lshlrev_b32_e32 v206, 16, v142
	v_and_b32_e32 v207, 0xffff0000, v142
	v_fmac_f32_e32 v203, v206, v206
	v_cvt_pk_bf16_f32 v143, v244, v245
	v_fmac_f32_e32 v203, v207, v207
	v_lshlrev_b32_e32 v208, 16, v143
	v_and_b32_e32 v209, 0xffff0000, v143
	v_fmac_f32_e32 v203, v208, v208
	v_fmac_f32_e32 v203, v209, v209
	v_lshlrev_b32_e32 v202, 16, v136
	v_and_b32_e32 v204, 0xffff0000, v136
	v_lshlrev_b32_e32 v205, 16, v137
	v_and_b32_e32 v206, 0xffff0000, v137
	v_lshlrev_b32_e32 v207, 16, v138
	v_and_b32_e32 v208, 0xffff0000, v138
	v_lshlrev_b32_e32 v209, 16, v139
	v_and_b32_e32 v210, 0xffff0000, v139
	v_pk_add_f32 v[136:137], v[94:95], v[200:201]
	v_pk_add_f32 v[138:139], v[92:93], v[198:199]
	v_pk_add_f32 v[198:199], v[90:91], v[196:197]
	v_pk_add_f32 v[196:197], v[88:89], v[194:195]
	v_fmac_f32_e32 v202, 0.5, v138
	v_fmac_f32_e32 v204, 0.5, v139
	v_cvt_pk_bf16_f32 v194, v202, v204
	v_fmac_f32_e32 v205, 0.5, v136
	v_lshlrev_b32_e32 v136, 16, v194
	v_fmac_f32_e32 v206, 0.5, v137
	v_and_b32_e32 v137, 0xffff0000, v194
	v_fmac_f32_e32 v203, v136, v136
	v_cvt_pk_bf16_f32 v195, v205, v206
	v_fmac_f32_e32 v203, v137, v137
	v_lshlrev_b32_e32 v138, 16, v195
	v_and_b32_e32 v139, 0xffff0000, v195
	v_fmac_f32_e32 v203, v138, v138
	v_fmac_f32_e32 v207, 0.5, v196
	v_fmac_f32_e32 v208, 0.5, v197
	v_cvt_pk_bf16_f32 v196, v207, v208
	v_fmac_f32_e32 v209, 0.5, v198
	v_lshlrev_b32_e32 v198, 16, v196
	v_fmac_f32_e32 v203, v139, v139
	v_and_b32_e32 v137, 64, v221
	v_fmac_f32_e32 v210, 0.5, v199
	v_and_b32_e32 v199, 0xffff0000, v196
	v_fmac_f32_e32 v203, v198, v198
	v_xor_b32_e32 v136, 16, v221
	v_add_u32_e32 v137, 64, v137
	v_cvt_pk_bf16_f32 v197, v209, v210
	v_fmac_f32_e32 v203, v199, v199
	v_lshlrev_b32_e32 v200, 16, v197
	v_cmp_lt_i32_e64 s[12:13], v136, v137
	v_and_b32_e32 v201, 0xffff0000, v197
	v_fmac_f32_e32 v203, v200, v200
	v_cndmask_b32_e64 v136, v221, v136, s[12:13]
	v_fmac_f32_e32 v203, v201, v201
	v_lshlrev_b32_e32 v237, 2, v136
	ds_bpermute_b32 v136, v237, v203
	v_xor_b32_e32 v138, 32, v221
	v_cmp_lt_i32_e64 s[12:13], v138, v137
	s_waitcnt lgkmcnt(0)
	v_add_f32_e32 v136, v203, v136
	v_cndmask_b32_e64 v137, v221, v138, s[12:13]
	v_lshlrev_b32_e32 v238, 2, v137
	ds_bpermute_b32 v137, v238, v136
	v_lshl_add_u64 v[138:139], s[28:29], 0, v[174:175]
	v_lshl_add_u64 v[138:139], v[168:169], 1, v[138:139]
	global_store_dwordx4 v[138:139], v[140:143], off sc1
	global_store_dwordx4 v[138:139], v[194:197], off offset:256 sc1
	s_and_saveexec_b64 s[12:13], s[8:9]
	s_cbranch_execz .LBB0_1408
	s_waitcnt lgkmcnt(0)
	v_add_f32_e32 v138, v136, v137
	v_lshl_add_u64 v[136:137], v[166:167], 2, s[14:15]
	global_atomic_add_f32 v[136:137], v138, off
; DI unsigned cvt_pk(float lo, float hi) { unsigned r; asm("v_cvt_pk_bf16_f32 %0, %1, %2" : "=v"(r) : "v"(lo), "v"(hi)); return r; }
;     __device__ __forceinline__ void operator()(const f32x4 (&acc)[2][2][4][2], const Unit& u, int wr, int wc, int fr, int fq) const {
;     ...
;                 for (int mm = 0; mm < 2; ++mm) {
;                     const int m = mp * 2 + mm;
;                     const int row = row0 + ai * HALF + m * 16;
;                     float s = 0.f;
; #pragma unroll
;                     for (int bj = 0; bj < 2; ++bj) {
;                         u32x4* px = (u32x4*)(X + (size_t)row * DM + col0 + bj * HALF);
;                         float xo[8]; unpack8(xin[mm][bj], xo);
;                         const f32x4 a0 = acc[ai][bj][m][0] + pv[mm][bj][0], a1 = acc[ai][bj][m][1] + pv[mm][bj][1];
;                         u32x4 w;
;                         w.x = cvt_pk(xo[0] + scale * a0[0], xo[1] + scale * a0[1]); w.y = cvt_pk(xo[2] + scale * a0[2], xo[3] + scale * a0[3]);
;                         w.z = cvt_pk(xo[4] + scale * a1[0], xo[5] + scale * a1[1]); w.w = cvt_pk(xo[6] + scale * a1[2], xo[7] + scale * a1[3]);
;                         *px = w;
;                         float xn[8]; unpack8(w, xn);
; #pragma unroll
;                         for (int j = 0; j < 8; ++j) s += xn[j] * xn[j];
;                     }
;                     s += __shfl_xor(s, 16); s += __shfl_xor(s, 32);
;                     if (fq == 0) unsafeAtomicAdd(ssn + row, s);
.LBB0_1408:
	s_or_b64 exec, exec, s[12:13]
	v_lshlrev_b32_e32 v140, 16, v132
	v_and_b32_e32 v141, 0xffff0000, v132
	v_lshlrev_b32_e32 v142, 16, v133
	v_and_b32_e32 v143, 0xffff0000, v133
	v_and_b32_e32 v197, 0xffff0000, v135
	v_pk_add_f32 v[132:133], v[116:117], v[190:191]
	s_waitcnt lgkmcnt(0)
	v_pk_add_f32 v[136:137], v[114:115], v[188:189]
	v_lshlrev_b32_e32 v196, 16, v135
	v_fmac_f32_e32 v140, 0.5, v132
	v_fmac_f32_e32 v141, 0.5, v133
	v_cvt_pk_bf16_f32 v132, v140, v141
	v_fmac_f32_e32 v197, 0.5, v137
	v_and_b32_e32 v137, 0xffff0000, v132
	v_lshlrev_b32_e32 v194, 16, v134
	v_and_b32_e32 v195, 0xffff0000, v134
	v_pk_add_f32 v[134:135], v[118:119], v[192:193]
	v_pk_add_f32 v[138:139], v[112:113], v[186:187]
	v_fmac_f32_e32 v196, 0.5, v136
	v_lshlrev_b32_e32 v136, 16, v132
	v_mul_f32_e32 v186, v137, v137
	v_fmac_f32_e32 v142, 0.5, v134
	v_fmac_f32_e32 v143, 0.5, v135
	v_cvt_pk_bf16_f32 v133, v142, v143
	v_fmac_f32_e32 v194, 0.5, v138
	v_lshlrev_b32_e32 v138, 16, v133
	v_fmac_f32_e32 v186, v136, v136
	v_fmac_f32_e32 v195, 0.5, v139
	v_and_b32_e32 v139, 0xffff0000, v133
	v_fmac_f32_e32 v186, v138, v138
	v_cvt_pk_bf16_f32 v134, v194, v195
	v_fmac_f32_e32 v186, v139, v139
	v_lshlrev_b32_e32 v140, 16, v134
	v_and_b32_e32 v141, 0xffff0000, v134
	v_fmac_f32_e32 v186, v140, v140
	v_cvt_pk_bf16_f32 v135, v196, v197
	v_fmac_f32_e32 v186, v141, v141
	v_lshlrev_b32_e32 v142, 16, v135
	v_and_b32_e32 v143, 0xffff0000, v135
	v_fmac_f32_e32 v186, v142, v142
	v_lshlrev_b32_e32 v136, 16, v128
	v_lshlrev_b32_e32 v187, 16, v130
	v_and_b32_e32 v188, 0xffff0000, v130
	v_lshlrev_b32_e32 v189, 16, v131
	v_and_b32_e32 v190, 0xffff0000, v131
	v_pk_add_f32 v[130:131], v[84:85], v[182:183]
	v_fmac_f32_e32 v186, v143, v143
	v_and_b32_e32 v137, 0xffff0000, v128
	v_lshlrev_b32_e32 v142, 16, v129
	v_and_b32_e32 v143, 0xffff0000, v129
	v_pk_add_f32 v[128:129], v[86:87], v[184:185]
	v_fmac_f32_e32 v136, 0.5, v130
	v_fmac_f32_e32 v137, 0.5, v131
	v_cvt_pk_bf16_f32 v136, v136, v137
	v_fmac_f32_e32 v142, 0.5, v128
	v_lshlrev_b32_e32 v128, 16, v136
	v_fmac_f32_e32 v143, 0.5, v129
	v_and_b32_e32 v129, 0xffff0000, v136
	v_fmac_f32_e32 v186, v128, v128
	v_cvt_pk_bf16_f32 v137, v142, v143
	v_fmac_f32_e32 v186, v129, v129
	v_lshlrev_b32_e32 v130, 16, v137
	v_pk_add_f32 v[140:141], v[82:83], v[180:181]
	v_pk_add_f32 v[138:139], v[80:81], v[178:179]
	v_and_b32_e32 v131, 0xffff0000, v137
	v_fmac_f32_e32 v186, v130, v130
	v_fmac_f32_e32 v187, 0.5, v138
	v_fmac_f32_e32 v188, 0.5, v139
	v_cvt_pk_bf16_f32 v138, v187, v188
	v_fmac_f32_e32 v189, 0.5, v140
	v_lshlrev_b32_e32 v140, 16, v138
	v_fmac_f32_e32 v186, v131, v131
	v_fmac_f32_e32 v190, 0.5, v141
	v_and_b32_e32 v141, 0xffff0000, v138
	v_fmac_f32_e32 v186, v140, v140
	v_cvt_pk_bf16_f32 v139, v189, v190
	v_fmac_f32_e32 v186, v141, v141
	v_lshlrev_b32_e32 v142, 16, v139
	v_and_b32_e32 v143, 0xffff0000, v139
	v_fmac_f32_e32 v186, v142, v142
	v_fmac_f32_e32 v186, v143, v143
	ds_bpermute_b32 v128, v237, v186
	v_lshl_add_u64 v[130:131], s[28:29], 0, v[176:177]
	v_lshl_add_u64 v[130:131], v[168:169], 1, v[130:131]
	global_store_dwordx4 v[130:131], v[132:135], off sc1
	global_store_dwordx4 v[130:131], v[136:139], off offset:256 sc1
	s_waitcnt lgkmcnt(0)
	v_add_f32_e32 v128, v186, v128
	ds_bpermute_b32 v129, v238, v128
	s_and_saveexec_b64 s[12:13], s[8:9]
	s_cbranch_execz .LBB0_1410
	s_waitcnt lgkmcnt(0)
	v_add_f32_e32 v130, v128, v129
	v_lshl_add_u64 v[128:129], v[166:167], 2, s[14:15]
	global_atomic_add_f32 v[128:129], v130, off offset:64

; DI unsigned cvt_pk(float lo, float hi) { unsigned r; asm("v_cvt_pk_bf16_f32 %0, %1, %2" : "=v"(r) : "v"(lo), "v"(hi)); return r; }
;     __device__ __forceinline__ void operator()(const f32x4 (&acc)[2][2][4][2], const Unit& u, int wr, int wc, int fr, int fq) const {
;     ...
;                 for (int mm = 0; mm < 2; ++mm) {
;                     const int m = mp * 2 + mm;
;                     const int row = row0 + ai * HALF + m * 16;
;                     float s = 0.f;
; #pragma unroll
;                     for (int bj = 0; bj < 2; ++bj) {
;                         u32x4* px = (u32x4*)(X + (size_t)row * DM + col0 + bj * HALF);
;                         float xo[8]; unpack8(xin[mm][bj], xo);
;                         const f32x4 a0 = acc[ai][bj][m][0] + pv[mm][bj][0], a1 = acc[ai][bj][m][1] + pv[mm][bj][1];
;                         u32x4 w;
;                         w.x = cvt_pk(xo[0] + scale * a0[0], xo[1] + scale * a0[1]); w.y = cvt_pk(xo[2] + scale * a0[2], xo[3] + scale * a0[3]);
;                         w.z = cvt_pk(xo[4] + scale * a1[0], xo[5] + scale * a1[1]); w.w = cvt_pk(xo[6] + scale * a1[2], xo[7] + scale * a1[3]);
;                         *px = w;
;                         float xn[8]; unpack8(w, xn);
; #pragma unroll
;                         for (int j = 0; j < 8; ++j) s += xn[j] * xn[j];
;                     }
;                     s += __shfl_xor(s, 16); s += __shfl_xor(s, 32);
;                     if (fq == 0) unsafeAtomicAdd(ssn + row, s);
.LBB0_1412:
	s_or_b64 exec, exec, s[12:13]
	s_waitcnt vmcnt(3)
	v_lshlrev_b32_e32 v214, 16, v140
	v_and_b32_e32 v215, 0xffff0000, v140
	v_lshlrev_b32_e32 v244, 16, v141
	v_and_b32_e32 v245, 0xffff0000, v141
	v_and_b32_e32 v247, 0xffff0000, v142
	v_pk_add_f32 v[140:141], v[108:109], v[208:209]
	v_pk_add_f32 v[204:205], v[104:105], v[204:205]
	v_lshlrev_b32_e32 v246, 16, v142
	v_fmac_f32_e32 v214, 0.5, v140
	v_fmac_f32_e32 v215, 0.5, v141
	v_cvt_pk_bf16_f32 v140, v214, v215
	v_fmac_f32_e32 v247, 0.5, v205
	v_and_b32_e32 v205, 0xffff0000, v140
	v_lshlrev_b32_e32 v248, 16, v143
	v_and_b32_e32 v249, 0xffff0000, v143
	v_pk_add_f32 v[142:143], v[110:111], v[210:211]
	v_pk_add_f32 v[206:207], v[106:107], v[206:207]
	v_fmac_f32_e32 v246, 0.5, v204
	v_lshlrev_b32_e32 v204, 16, v140
	v_mul_f32_e32 v205, v205, v205
	v_fmac_f32_e32 v244, 0.5, v142
	v_fmac_f32_e32 v245, 0.5, v143
	v_cvt_pk_bf16_f32 v141, v244, v245
	v_fmac_f32_e32 v248, 0.5, v206
	v_lshlrev_b32_e32 v206, 16, v141
	v_fmac_f32_e32 v205, v204, v204
	v_fmac_f32_e32 v249, 0.5, v207
	v_and_b32_e32 v207, 0xffff0000, v141
	v_fmac_f32_e32 v205, v206, v206
	v_cvt_pk_bf16_f32 v142, v246, v247
	v_fmac_f32_e32 v205, v207, v207
	v_lshlrev_b32_e32 v208, 16, v142
	v_and_b32_e32 v209, 0xffff0000, v142
	v_fmac_f32_e32 v205, v208, v208
	v_cvt_pk_bf16_f32 v143, v248, v249
	v_fmac_f32_e32 v205, v209, v209
	v_lshlrev_b32_e32 v210, 16, v143
	v_and_b32_e32 v211, 0xffff0000, v143
	v_fmac_f32_e32 v205, v210, v210
	v_fmac_f32_e32 v205, v211, v211
	s_waitcnt vmcnt(2)
	v_lshlrev_b32_e32 v204, 16, v136
	v_and_b32_e32 v206, 0xffff0000, v136
	v_lshlrev_b32_e32 v207, 16, v137
	v_and_b32_e32 v208, 0xffff0000, v137
	v_lshlrev_b32_e32 v209, 16, v138
	v_and_b32_e32 v210, 0xffff0000, v138
	v_lshlrev_b32_e32 v211, 16, v139
	v_and_b32_e32 v214, 0xffff0000, v139
	v_pk_add_f32 v[136:137], v[78:79], v[202:203]
	v_pk_add_f32 v[138:139], v[76:77], v[200:201]
	v_pk_add_f32 v[200:201], v[74:75], v[198:199]
	v_pk_add_f32 v[198:199], v[72:73], v[196:197]
	v_fmac_f32_e32 v204, 0.5, v138
	v_fmac_f32_e32 v206, 0.5, v139
	v_cvt_pk_bf16_f32 v196, v204, v206
	v_fmac_f32_e32 v207, 0.5, v136
	v_lshlrev_b32_e32 v136, 16, v196
	v_fmac_f32_e32 v208, 0.5, v137
	v_and_b32_e32 v137, 0xffff0000, v196
	v_fmac_f32_e32 v205, v136, v136
	v_cvt_pk_bf16_f32 v197, v207, v208
	v_fmac_f32_e32 v205, v137, v137
	v_lshlrev_b32_e32 v138, 16, v197
	v_and_b32_e32 v139, 0xffff0000, v197
	v_fmac_f32_e32 v205, v138, v138
	v_fmac_f32_e32 v209, 0.5, v198
	v_fmac_f32_e32 v210, 0.5, v199
	v_cvt_pk_bf16_f32 v198, v209, v210
	v_fmac_f32_e32 v211, 0.5, v200
	v_lshlrev_b32_e32 v200, 16, v198
	v_fmac_f32_e32 v205, v139, v139
	v_fmac_f32_e32 v214, 0.5, v201
	v_and_b32_e32 v201, 0xffff0000, v198
	v_fmac_f32_e32 v205, v200, v200
	v_cvt_pk_bf16_f32 v199, v211, v214
	v_fmac_f32_e32 v205, v201, v201
	v_lshlrev_b32_e32 v202, 16, v199
	v_and_b32_e32 v203, 0xffff0000, v199
	v_fmac_f32_e32 v205, v202, v202
	v_fmac_f32_e32 v205, v203, v203
	ds_bpermute_b32 v136, v237, v205
	v_lshl_add_u64 v[138:139], s[28:29], 0, v[186:187]
	v_lshl_add_u64 v[138:139], v[168:169], 1, v[138:139]
	global_store_dwordx4 v[138:139], v[140:143], off sc1
	global_store_dwordx4 v[138:139], v[196:199], off offset:256 sc1
	s_waitcnt lgkmcnt(0)
	v_add_f32_e32 v136, v205, v136
	ds_bpermute_b32 v137, v238, v136
	s_and_saveexec_b64 s[12:13], s[8:9]
	s_cbranch_execz .LBB0_1414
	s_waitcnt lgkmcnt(0)
	v_add_f32_e32 v138, v136, v137
	v_lshl_add_u64 v[136:137], v[166:167], 2, s[14:15]
	global_atomic_add_f32 v[136:137], v138, off offset:128
; DI unsigned cvt_pk(float lo, float hi) { unsigned r; asm("v_cvt_pk_bf16_f32 %0, %1, %2" : "=v"(r) : "v"(lo), "v"(hi)); return r; }
;     __device__ __forceinline__ void operator()(const f32x4 (&acc)[2][2][4][2], const Unit& u, int wr, int wc, int fr, int fq) const {
;     ...
;                 for (int mm = 0; mm < 2; ++mm) {
;                     const int m = mp * 2 + mm;
;                     const int row = row0 + ai * HALF + m * 16;
;                     float s = 0.f;
; #pragma unroll
;                     for (int bj = 0; bj < 2; ++bj) {
;                         u32x4* px = (u32x4*)(X + (size_t)row * DM + col0 + bj * HALF);
;                         float xo[8]; unpack8(xin[mm][bj], xo);
;                         const f32x4 a0 = acc[ai][bj][m][0] + pv[mm][bj][0], a1 = acc[ai][bj][m][1] + pv[mm][bj][1];
;                         u32x4 w;
;                         w.x = cvt_pk(xo[0] + scale * a0[0], xo[1] + scale * a0[1]); w.y = cvt_pk(xo[2] + scale * a0[2], xo[3] + scale * a0[3]);
;                         w.z = cvt_pk(xo[4] + scale * a1[0], xo[5] + scale * a1[1]); w.w = cvt_pk(xo[6] + scale * a1[2], xo[7] + scale * a1[3]);
;                         *px = w;
;                         float xn[8]; unpack8(w, xn);
; #pragma unroll
;                         for (int j = 0; j < 8; ++j) s += xn[j] * xn[j];
;                     }
;                     s += __shfl_xor(s, 16); s += __shfl_xor(s, 32);
;                     if (fq == 0) unsafeAtomicAdd(ssn + row, s);
.LBB0_1414:
	s_or_b64 exec, exec, s[12:13]
	s_waitcnt vmcnt(3)
	v_lshlrev_b32_e32 v140, 16, v132
	v_and_b32_e32 v141, 0xffff0000, v132
	v_lshlrev_b32_e32 v142, 16, v133
	v_and_b32_e32 v143, 0xffff0000, v133
	v_lshlrev_b32_e32 v186, 16, v134
	v_and_b32_e32 v197, 0xffff0000, v135
	v_pk_add_f32 v[132:133], v[100:101], v[192:193]
	s_waitcnt lgkmcnt(0)
	v_pk_add_f32 v[136:137], v[98:99], v[190:191]
	v_pk_add_f32 v[138:139], v[96:97], v[188:189]
	v_and_b32_e32 v187, 0xffff0000, v134
	v_lshlrev_b32_e32 v196, 16, v135
	v_pk_add_f32 v[134:135], v[102:103], v[194:195]
	v_fmac_f32_e32 v140, 0.5, v132
	v_fmac_f32_e32 v141, 0.5, v133
	v_cvt_pk_bf16_f32 v132, v140, v141
	v_fmac_f32_e32 v186, 0.5, v138
	v_fmac_f32_e32 v197, 0.5, v137
	v_and_b32_e32 v137, 0xffff0000, v132
	v_fmac_f32_e32 v142, 0.5, v134
	v_fmac_f32_e32 v187, 0.5, v139
	v_cvt_pk_bf16_f32 v134, v186, v187
	v_fmac_f32_e32 v196, 0.5, v136
	v_lshlrev_b32_e32 v136, 16, v132
	v_mul_f32_e32 v186, v137, v137
	v_fmac_f32_e32 v143, 0.5, v135
	v_cvt_pk_bf16_f32 v133, v142, v143
	v_fmac_f32_e32 v186, v136, v136
	v_lshlrev_b32_e32 v138, 16, v133
	v_and_b32_e32 v139, 0xffff0000, v133
	v_fmac_f32_e32 v186, v138, v138
	v_lshlrev_b32_e32 v140, 16, v134
	v_fmac_f32_e32 v186, v139, v139
	v_and_b32_e32 v141, 0xffff0000, v134
	v_fmac_f32_e32 v186, v140, v140
	v_cvt_pk_bf16_f32 v135, v196, v197
	v_fmac_f32_e32 v186, v141, v141
	v_lshlrev_b32_e32 v142, 16, v135
	v_and_b32_e32 v143, 0xffff0000, v135
	v_fmac_f32_e32 v186, v142, v142
	s_waitcnt vmcnt(2)
	v_lshlrev_b32_e32 v136, 16, v128
	v_lshlrev_b32_e32 v187, 16, v130
	v_and_b32_e32 v188, 0xffff0000, v130
	v_lshlrev_b32_e32 v189, 16, v131
	v_and_b32_e32 v190, 0xffff0000, v131
	v_pk_add_f32 v[130:131], v[68:69], v[182:183]
	v_fmac_f32_e32 v186, v143, v143
	v_and_b32_e32 v137, 0xffff0000, v128
	v_lshlrev_b32_e32 v142, 16, v129
	v_and_b32_e32 v143, 0xffff0000, v129
	v_pk_add_f32 v[128:129], v[70:71], v[184:185]
	v_fmac_f32_e32 v136, 0.5, v130
	v_fmac_f32_e32 v137, 0.5, v131
	v_cvt_pk_bf16_f32 v136, v136, v137
	v_fmac_f32_e32 v142, 0.5, v128
	v_lshlrev_b32_e32 v128, 16, v136
	v_fmac_f32_e32 v143, 0.5, v129
	v_and_b32_e32 v129, 0xffff0000, v136
	v_fmac_f32_e32 v186, v128, v128
	v_cvt_pk_bf16_f32 v137, v142, v143
	v_fmac_f32_e32 v186, v129, v129
	v_lshlrev_b32_e32 v130, 16, v137
	v_pk_add_f32 v[140:141], v[66:67], v[180:181]
	v_pk_add_f32 v[138:139], v[64:65], v[178:179]
	v_and_b32_e32 v131, 0xffff0000, v137
	v_fmac_f32_e32 v186, v130, v130
	v_fmac_f32_e32 v187, 0.5, v138
	v_fmac_f32_e32 v188, 0.5, v139
	v_cvt_pk_bf16_f32 v138, v187, v188
	v_fmac_f32_e32 v189, 0.5, v140
	v_lshlrev_b32_e32 v140, 16, v138
	v_fmac_f32_e32 v186, v131, v131
	v_fmac_f32_e32 v190, 0.5, v141
	v_and_b32_e32 v141, 0xffff0000, v138
	v_fmac_f32_e32 v186, v140, v140
	v_cvt_pk_bf16_f32 v139, v189, v190
	v_fmac_f32_e32 v186, v141, v141
	v_lshlrev_b32_e32 v142, 16, v139
	v_and_b32_e32 v143, 0xffff0000, v139
	v_fmac_f32_e32 v186, v142, v142
	v_fmac_f32_e32 v186, v143, v143
	ds_bpermute_b32 v128, v237, v186
	v_lshl_add_u64 v[130:131], s[28:29], 0, v[176:177]
	v_lshl_add_u64 v[130:131], v[168:169], 1, v[130:131]
	global_store_dwordx4 v[130:131], v[132:135], off sc1
	global_store_dwordx4 v[130:131], v[136:139], off offset:256 sc1
	s_waitcnt lgkmcnt(0)
	v_add_f32_e32 v128, v186, v128
	ds_bpermute_b32 v129, v238, v128
	s_and_saveexec_b64 s[12:13], s[8:9]
	s_cbranch_execz .LBB0_1416
	s_waitcnt lgkmcnt(0)
	v_add_f32_e32 v130, v128, v129
	v_lshl_add_u64 v[128:129], v[166:167], 2, s[14:15]
	global_atomic_add_f32 v[128:129], v130, off offset:192

; DI unsigned cvt_pk(float lo, float hi) { unsigned r; asm("v_cvt_pk_bf16_f32 %0, %1, %2" : "=v"(r) : "v"(lo), "v"(hi)); return r; }
;     __device__ __forceinline__ void operator()(const f32x4 (&acc)[2][2][4][2], const Unit& u, int wr, int wc, int fr, int fq) const {
;     ...
;                 for (int mm = 0; mm < 2; ++mm) {
;                     const int m = mp * 2 + mm;
;                     const int row = row0 + ai * HALF + m * 16;
;                     float s = 0.f;
; #pragma unroll
;                     for (int bj = 0; bj < 2; ++bj) {
;                         u32x4* px = (u32x4*)(X + (size_t)row * DM + col0 + bj * HALF);
;                         float xo[8]; unpack8(xin[mm][bj], xo);
;                         const f32x4 a0 = acc[ai][bj][m][0] + pv[mm][bj][0], a1 = acc[ai][bj][m][1] + pv[mm][bj][1];
;                         u32x4 w;
;                         w.x = cvt_pk(xo[0] + scale * a0[0], xo[1] + scale * a0[1]); w.y = cvt_pk(xo[2] + scale * a0[2], xo[3] + scale * a0[3]);
;                         w.z = cvt_pk(xo[4] + scale * a1[0], xo[5] + scale * a1[1]); w.w = cvt_pk(xo[6] + scale * a1[2], xo[7] + scale * a1[3]);
;                         *px = w;
;                         float xn[8]; unpack8(w, xn);
; #pragma unroll
;                         for (int j = 0; j < 8; ++j) s += xn[j] * xn[j];
;                     }
;                     s += __shfl_xor(s, 16); s += __shfl_xor(s, 32);
;                     if (fq == 0) unsafeAtomicAdd(ssn + row, s);
.LBB0_1418:
	s_or_b64 exec, exec, s[12:13]
	s_waitcnt vmcnt(3)
	v_lshlrev_b32_e32 v214, 16, v140
	v_and_b32_e32 v215, 0xffff0000, v140
	v_lshlrev_b32_e32 v244, 16, v141
	v_and_b32_e32 v245, 0xffff0000, v141
	v_and_b32_e32 v247, 0xffff0000, v142
	v_pk_add_f32 v[140:141], v[60:61], v[208:209]
	v_pk_add_f32 v[204:205], v[56:57], v[204:205]
	v_lshlrev_b32_e32 v246, 16, v142
	v_fmac_f32_e32 v214, 0.5, v140
	v_fmac_f32_e32 v215, 0.5, v141
	v_cvt_pk_bf16_f32 v140, v214, v215
	v_fmac_f32_e32 v247, 0.5, v205
	v_and_b32_e32 v205, 0xffff0000, v140
	v_lshlrev_b32_e32 v248, 16, v143
	v_and_b32_e32 v249, 0xffff0000, v143
	v_pk_add_f32 v[142:143], v[62:63], v[210:211]
	v_pk_add_f32 v[206:207], v[58:59], v[206:207]
	v_fmac_f32_e32 v246, 0.5, v204
	v_lshlrev_b32_e32 v204, 16, v140
	v_mul_f32_e32 v205, v205, v205
	v_fmac_f32_e32 v244, 0.5, v142
	v_fmac_f32_e32 v245, 0.5, v143
	v_cvt_pk_bf16_f32 v141, v244, v245
	v_fmac_f32_e32 v248, 0.5, v206
	v_lshlrev_b32_e32 v206, 16, v141
	v_fmac_f32_e32 v205, v204, v204
	v_fmac_f32_e32 v249, 0.5, v207
	v_and_b32_e32 v207, 0xffff0000, v141
	v_fmac_f32_e32 v205, v206, v206
	v_cvt_pk_bf16_f32 v142, v246, v247
	v_fmac_f32_e32 v205, v207, v207
	v_lshlrev_b32_e32 v208, 16, v142
	v_and_b32_e32 v209, 0xffff0000, v142
	v_fmac_f32_e32 v205, v208, v208
	v_cvt_pk_bf16_f32 v143, v248, v249
	v_fmac_f32_e32 v205, v209, v209
	v_lshlrev_b32_e32 v210, 16, v143
	v_and_b32_e32 v211, 0xffff0000, v143
	v_fmac_f32_e32 v205, v210, v210
	v_fmac_f32_e32 v205, v211, v211
	s_waitcnt vmcnt(2)
	v_lshlrev_b32_e32 v204, 16, v136
	v_and_b32_e32 v206, 0xffff0000, v136
	v_lshlrev_b32_e32 v207, 16, v137
	v_and_b32_e32 v208, 0xffff0000, v137
	v_lshlrev_b32_e32 v209, 16, v138
	v_and_b32_e32 v210, 0xffff0000, v138
	v_lshlrev_b32_e32 v211, 16, v139
	v_and_b32_e32 v214, 0xffff0000, v139
	v_pk_add_f32 v[136:137], v[30:31], v[202:203]
	v_pk_add_f32 v[138:139], v[28:29], v[200:201]
	v_pk_add_f32 v[200:201], v[26:27], v[198:199]
	v_pk_add_f32 v[198:199], v[24:25], v[196:197]
	v_fmac_f32_e32 v204, 0.5, v138
	v_fmac_f32_e32 v206, 0.5, v139
	v_cvt_pk_bf16_f32 v196, v204, v206
	v_fmac_f32_e32 v207, 0.5, v136
	v_lshlrev_b32_e32 v136, 16, v196
	v_fmac_f32_e32 v208, 0.5, v137
	v_and_b32_e32 v137, 0xffff0000, v196
	v_fmac_f32_e32 v205, v136, v136
	v_cvt_pk_bf16_f32 v197, v207, v208
	v_fmac_f32_e32 v205, v137, v137
	v_lshlrev_b32_e32 v138, 16, v197
	v_and_b32_e32 v139, 0xffff0000, v197
	v_fmac_f32_e32 v205, v138, v138
	v_fmac_f32_e32 v209, 0.5, v198
	v_fmac_f32_e32 v210, 0.5, v199
	v_cvt_pk_bf16_f32 v198, v209, v210
	v_fmac_f32_e32 v211, 0.5, v200
	v_lshlrev_b32_e32 v200, 16, v198
	v_fmac_f32_e32 v205, v139, v139
	v_fmac_f32_e32 v214, 0.5, v201
	v_and_b32_e32 v201, 0xffff0000, v198
	v_fmac_f32_e32 v205, v200, v200
	v_cvt_pk_bf16_f32 v199, v211, v214
	v_fmac_f32_e32 v205, v201, v201
	v_lshlrev_b32_e32 v202, 16, v199
	v_and_b32_e32 v203, 0xffff0000, v199
	v_fmac_f32_e32 v205, v202, v202
	v_fmac_f32_e32 v205, v203, v203
	ds_bpermute_b32 v136, v237, v205
	v_lshl_add_u64 v[138:139], s[28:29], 0, v[186:187]
	v_lshl_add_u64 v[138:139], v[168:169], 1, v[138:139]
	global_store_dwordx4 v[138:139], v[140:143], off sc1
	global_store_dwordx4 v[138:139], v[196:199], off offset:256 sc1
	s_waitcnt lgkmcnt(0)
	v_add_f32_e32 v136, v205, v136
	ds_bpermute_b32 v137, v238, v136
	s_and_saveexec_b64 s[12:13], s[8:9]
	s_cbranch_execz .LBB0_1420
	s_waitcnt lgkmcnt(0)
	v_add_f32_e32 v138, v136, v137
	v_lshl_add_u64 v[136:137], v[166:167], 2, s[14:15]
	global_atomic_add_f32 v[136:137], v138, off offset:512
.LBB0_1420:
	s_or_b64 exec, exec, s[12:13]
	s_waitcnt vmcnt(3)
	v_lshlrev_b32_e32 v140, 16, v132
	v_and_b32_e32 v141, 0xffff0000, v132
	v_lshlrev_b32_e32 v142, 16, v133
	v_and_b32_e32 v143, 0xffff0000, v133
	v_lshlrev_b32_e32 v186, 16, v134
	v_and_b32_e32 v197, 0xffff0000, v135
	v_pk_add_f32 v[132:133], v[52:53], v[192:193]
	s_waitcnt lgkmcnt(0)
	v_pk_add_f32 v[136:137], v[50:51], v[190:191]
	v_pk_add_f32 v[138:139], v[48:49], v[188:189]
	v_and_b32_e32 v187, 0xffff0000, v134
	v_lshlrev_b32_e32 v196, 16, v135
	v_pk_add_f32 v[134:135], v[54:55], v[194:195]
	v_fmac_f32_e32 v140, 0.5, v132
	v_fmac_f32_e32 v141, 0.5, v133
	v_cvt_pk_bf16_f32 v132, v140, v141
	v_fmac_f32_e32 v186, 0.5, v138
	v_fmac_f32_e32 v197, 0.5, v137
	v_and_b32_e32 v137, 0xffff0000, v132
	v_fmac_f32_e32 v142, 0.5, v134
	v_fmac_f32_e32 v187, 0.5, v139
	v_cvt_pk_bf16_f32 v134, v186, v187
	v_fmac_f32_e32 v196, 0.5, v136
	v_lshlrev_b32_e32 v136, 16, v132
	v_mul_f32_e32 v186, v137, v137
	v_fmac_f32_e32 v143, 0.5, v135
	v_cvt_pk_bf16_f32 v133, v142, v143
	v_fmac_f32_e32 v186, v136, v136
	v_lshlrev_b32_e32 v138, 16, v133
	v_and_b32_e32 v139, 0xffff0000, v133
	v_fmac_f32_e32 v186, v138, v138
	v_lshlrev_b32_e32 v140, 16, v134
	v_fmac_f32_e32 v186, v139, v139
	v_and_b32_e32 v141, 0xffff0000, v134
	v_fmac_f32_e32 v186, v140, v140
	v_cvt_pk_bf16_f32 v135, v196, v197
	v_fmac_f32_e32 v186, v141, v141
	v_lshlrev_b32_e32 v142, 16, v135
	v_and_b32_e32 v143, 0xffff0000, v135
	v_fmac_f32_e32 v186, v142, v142
	s_waitcnt vmcnt(2)
	v_lshlrev_b32_e32 v136, 16, v128
	v_lshlrev_b32_e32 v187, 16, v130
	v_and_b32_e32 v188, 0xffff0000, v130
	v_lshlrev_b32_e32 v189, 16, v131
	v_and_b32_e32 v190, 0xffff0000, v131
	v_pk_add_f32 v[130:131], v[20:21], v[182:183]
	v_fmac_f32_e32 v186, v143, v143
	v_and_b32_e32 v137, 0xffff0000, v128
	v_lshlrev_b32_e32 v142, 16, v129
	v_and_b32_e32 v143, 0xffff0000, v129
	v_pk_add_f32 v[128:129], v[22:23], v[184:185]
	v_fmac_f32_e32 v136, 0.5, v130
	v_fmac_f32_e32 v137, 0.5, v131
	v_cvt_pk_bf16_f32 v136, v136, v137
	v_fmac_f32_e32 v142, 0.5, v128
	v_lshlrev_b32_e32 v128, 16, v136
	v_fmac_f32_e32 v143, 0.5, v129
	v_and_b32_e32 v129, 0xffff0000, v136
	v_fmac_f32_e32 v186, v128, v128
	v_cvt_pk_bf16_f32 v137, v142, v143
	v_fmac_f32_e32 v186, v129, v129
	v_lshlrev_b32_e32 v130, 16, v137
	v_pk_add_f32 v[140:141], v[18:19], v[180:181]
	v_pk_add_f32 v[138:139], v[16:17], v[178:179]
	v_and_b32_e32 v131, 0xffff0000, v137
	v_fmac_f32_e32 v186, v130, v130
	v_fmac_f32_e32 v187, 0.5, v138
	v_fmac_f32_e32 v188, 0.5, v139
	v_cvt_pk_bf16_f32 v138, v187, v188
	v_fmac_f32_e32 v189, 0.5, v140
	v_lshlrev_b32_e32 v140, 16, v138
	v_fmac_f32_e32 v186, v131, v131
	v_fmac_f32_e32 v190, 0.5, v141
	v_and_b32_e32 v141, 0xffff0000, v138
	v_fmac_f32_e32 v186, v140, v140
	v_cvt_pk_bf16_f32 v139, v189, v190
	v_fmac_f32_e32 v186, v141, v141
	v_lshlrev_b32_e32 v142, 16, v139
	v_and_b32_e32 v143, 0xffff0000, v139
	v_fmac_f32_e32 v186, v142, v142
	v_fmac_f32_e32 v186, v143, v143
	ds_bpermute_b32 v128, v237, v186
	v_lshl_add_u64 v[130:131], s[28:29], 0, v[176:177]
	v_lshl_add_u64 v[130:131], v[168:169], 1, v[130:131]
	global_store_dwordx4 v[130:131], v[132:135], off sc1
	global_store_dwordx4 v[130:131], v[136:139], off offset:256 sc1
	s_waitcnt lgkmcnt(0)
	v_add_f32_e32 v128, v186, v128
	ds_bpermute_b32 v129, v238, v128
	s_and_saveexec_b64 s[12:13], s[8:9]
	s_cbranch_execz .LBB0_1422
	s_waitcnt lgkmcnt(0)
	v_add_f32_e32 v130, v128, v129
	v_lshl_add_u64 v[128:129], v[166:167], 2, s[14:15]
	global_atomic_add_f32 v[128:129], v130, off offset:576

; DI unsigned cvt_pk(float lo, float hi) { unsigned r; asm("v_cvt_pk_bf16_f32 %0, %1, %2" : "=v"(r) : "v"(lo), "v"(hi)); return r; }
;     __device__ __forceinline__ void operator()(const f32x4 (&acc)[2][2][4][2], const Unit& u, int wr, int wc, int fr, int fq) const {
;     ...
; #pragma unroll
;                 for (int mm = 0; mm < 2; ++mm) {
;                     const int m = mp * 2 + mm;
;                     const int row = row0 + ai * HALF + m * 16;
;                     float s = 0.f;
; #pragma unroll
;                     for (int bj = 0; bj < 2; ++bj) {
;                         u32x4* px = (u32x4*)(X + (size_t)row * DM + col0 + bj * HALF);
;                         float xo[8]; unpack8(xin[mm][bj], xo);
;                         const f32x4 a0 = acc[ai][bj][m][0] + pv[mm][bj][0], a1 = acc[ai][bj][m][1] + pv[mm][bj][1];
;                         u32x4 w;
;                         w.x = cvt_pk(xo[0] + scale * a0[0], xo[1] + scale * a0[1]); w.y = cvt_pk(xo[2] + scale * a0[2], xo[3] + scale * a0[3]);
;                         w.z = cvt_pk(xo[4] + scale * a1[0], xo[5] + scale * a1[1]); w.w = cvt_pk(xo[6] + scale * a1[2], xo[7] + scale * a1[3]);
;                         *px = w;
;                         float xn[8]; unpack8(w, xn);
; #pragma unroll
;                         for (int j = 0; j < 8; ++j) s += xn[j] * xn[j];
;                     }
;                     s += __shfl_xor(s, 16); s += __shfl_xor(s, 32);
;                     if (fq == 0) unsafeAtomicAdd(ssn + row, s);
;                 }
.LBB0_1424:
	s_or_b64 exec, exec, s[12:13]
	s_waitcnt vmcnt(3)
	v_lshlrev_b32_e32 v208, 16, v140
	v_and_b32_e32 v209, 0xffff0000, v140
	v_lshlrev_b32_e32 v210, 16, v141
	v_and_b32_e32 v211, 0xffff0000, v141
	v_and_b32_e32 v245, 0xffff0000, v143
	v_pk_add_f32 v[140:141], v[44:45], v[204:205]
	v_pk_add_f32 v[170:171], v[42:43], v[202:203]
	v_lshlrev_b32_e32 v244, 16, v143
	v_fmac_f32_e32 v208, 0.5, v140
	v_fmac_f32_e32 v209, 0.5, v141
	v_cvt_pk_bf16_f32 v140, v208, v209
	v_fmac_f32_e32 v245, 0.5, v171
	v_and_b32_e32 v171, 0xffff0000, v140
	v_lshlrev_b32_e32 v214, 16, v142
	v_and_b32_e32 v215, 0xffff0000, v142
	v_pk_add_f32 v[142:143], v[46:47], v[206:207]
	v_pk_add_f32 v[200:201], v[40:41], v[200:201]
	v_fmac_f32_e32 v244, 0.5, v170
	v_lshlrev_b32_e32 v170, 16, v140
	v_mul_f32_e32 v206, v171, v171
	v_fmac_f32_e32 v210, 0.5, v142
	v_fmac_f32_e32 v211, 0.5, v143
	v_cvt_pk_bf16_f32 v141, v210, v211
	v_fmac_f32_e32 v214, 0.5, v200
	v_lshlrev_b32_e32 v200, 16, v141
	v_fmac_f32_e32 v206, v170, v170
	v_fmac_f32_e32 v215, 0.5, v201
	v_and_b32_e32 v201, 0xffff0000, v141
	v_fmac_f32_e32 v206, v200, v200
	v_cvt_pk_bf16_f32 v142, v214, v215
	v_fmac_f32_e32 v206, v201, v201
	v_lshlrev_b32_e32 v202, 16, v142
	v_and_b32_e32 v203, 0xffff0000, v142
	v_fmac_f32_e32 v206, v202, v202
	v_cvt_pk_bf16_f32 v143, v244, v245
	v_fmac_f32_e32 v206, v203, v203
	v_lshlrev_b32_e32 v204, 16, v143
	v_and_b32_e32 v205, 0xffff0000, v143
	v_fmac_f32_e32 v206, v204, v204
	v_fmac_f32_e32 v206, v205, v205
	s_waitcnt vmcnt(2)
	v_lshlrev_b32_e32 v200, 16, v136
	v_and_b32_e32 v201, 0xffff0000, v136
	v_lshlrev_b32_e32 v202, 16, v137
	v_and_b32_e32 v203, 0xffff0000, v137
	v_lshlrev_b32_e32 v204, 16, v138
	v_and_b32_e32 v205, 0xffff0000, v138
	v_lshlrev_b32_e32 v207, 16, v139
	v_and_b32_e32 v208, 0xffff0000, v139
	v_pk_add_f32 v[136:137], v[14:15], v[198:199]
	v_pk_add_f32 v[138:139], v[12:13], v[196:197]
	v_pk_add_f32 v[170:171], v[10:11], v[194:195]
	v_pk_add_f32 v[194:195], v[8:9], v[192:193]
	v_fmac_f32_e32 v200, 0.5, v138
	v_fmac_f32_e32 v201, 0.5, v139
	v_cvt_pk_bf16_f32 v192, v200, v201
	v_fmac_f32_e32 v202, 0.5, v136
	v_lshlrev_b32_e32 v136, 16, v192
	v_fmac_f32_e32 v203, 0.5, v137
	v_and_b32_e32 v137, 0xffff0000, v192
	v_fmac_f32_e32 v206, v136, v136
	v_cvt_pk_bf16_f32 v193, v202, v203
	v_fmac_f32_e32 v206, v137, v137
	v_lshlrev_b32_e32 v138, 16, v193
	v_and_b32_e32 v139, 0xffff0000, v193
	v_fmac_f32_e32 v206, v138, v138
	v_fmac_f32_e32 v204, 0.5, v194
	v_fmac_f32_e32 v205, 0.5, v195
	v_cvt_pk_bf16_f32 v194, v204, v205
	v_fmac_f32_e32 v207, 0.5, v170
	v_lshlrev_b32_e32 v170, 16, v194
	v_fmac_f32_e32 v206, v139, v139
	v_fmac_f32_e32 v208, 0.5, v171
	v_and_b32_e32 v171, 0xffff0000, v194
	v_fmac_f32_e32 v206, v170, v170
	v_cvt_pk_bf16_f32 v195, v207, v208
	v_fmac_f32_e32 v206, v171, v171
	v_lshlrev_b32_e32 v196, 16, v195
	v_and_b32_e32 v197, 0xffff0000, v195
	v_fmac_f32_e32 v206, v196, v196
	v_fmac_f32_e32 v206, v197, v197
	ds_bpermute_b32 v136, v237, v206
	v_lshl_add_u64 v[138:139], s[28:29], 0, v[182:183]
	v_lshl_add_u64 v[138:139], v[168:169], 1, v[138:139]
	global_store_dwordx4 v[138:139], v[140:143], off sc1
	global_store_dwordx4 v[138:139], v[192:195], off offset:256 sc1
	s_waitcnt lgkmcnt(0)
	v_add_f32_e32 v136, v206, v136
	ds_bpermute_b32 v137, v238, v136
	s_and_saveexec_b64 s[12:13], s[8:9]
	s_cbranch_execz .LBB0_1426
	s_waitcnt lgkmcnt(0)
	v_add_f32_e32 v138, v136, v137
	v_lshl_add_u64 v[136:137], v[166:167], 2, s[14:15]
	global_atomic_add_f32 v[136:137], v138, off offset:640
.LBB0_1426:
	s_or_b64 exec, exec, s[12:13]
	s_waitcnt vmcnt(3)
	v_lshlrev_b32_e32 v140, 16, v132
	v_and_b32_e32 v141, 0xffff0000, v132
	v_lshlrev_b32_e32 v142, 16, v133
	v_and_b32_e32 v143, 0xffff0000, v133
	v_lshlrev_b32_e32 v170, 16, v134
	v_and_b32_e32 v183, 0xffff0000, v135
	v_pk_add_f32 v[132:133], v[36:37], v[188:189]
	s_waitcnt lgkmcnt(0)
	v_pk_add_f32 v[136:137], v[34:35], v[186:187]
	v_pk_add_f32 v[138:139], v[32:33], v[184:185]
	v_and_b32_e32 v171, 0xffff0000, v134
	v_lshlrev_b32_e32 v182, 16, v135
	v_pk_add_f32 v[134:135], v[38:39], v[190:191]
	v_fmac_f32_e32 v140, 0.5, v132
	v_fmac_f32_e32 v141, 0.5, v133
	v_cvt_pk_bf16_f32 v132, v140, v141
	v_fmac_f32_e32 v170, 0.5, v138
	v_fmac_f32_e32 v183, 0.5, v137
	v_and_b32_e32 v137, 0xffff0000, v132
	v_fmac_f32_e32 v142, 0.5, v134
	v_fmac_f32_e32 v171, 0.5, v139
	v_cvt_pk_bf16_f32 v134, v170, v171
	v_fmac_f32_e32 v182, 0.5, v136
	v_lshlrev_b32_e32 v136, 16, v132
	v_mul_f32_e32 v170, v137, v137
	v_fmac_f32_e32 v143, 0.5, v135
	v_cvt_pk_bf16_f32 v133, v142, v143
	v_fmac_f32_e32 v170, v136, v136
	v_lshlrev_b32_e32 v138, 16, v133
	v_and_b32_e32 v139, 0xffff0000, v133
	v_fmac_f32_e32 v170, v138, v138
	v_lshlrev_b32_e32 v140, 16, v134
	v_fmac_f32_e32 v170, v139, v139
	v_and_b32_e32 v141, 0xffff0000, v134
	v_fmac_f32_e32 v170, v140, v140
	v_cvt_pk_bf16_f32 v135, v182, v183
	v_fmac_f32_e32 v170, v141, v141
	v_lshlrev_b32_e32 v142, 16, v135
	v_and_b32_e32 v143, 0xffff0000, v135
	v_fmac_f32_e32 v170, v142, v142
	s_waitcnt vmcnt(2)
	v_lshlrev_b32_e32 v136, 16, v128
	v_lshlrev_b32_e32 v171, 16, v130
	v_and_b32_e32 v182, 0xffff0000, v130
	v_lshlrev_b32_e32 v183, 16, v131
	v_and_b32_e32 v184, 0xffff0000, v131
	v_pk_add_f32 v[130:131], v[4:5], v[178:179]
	v_fmac_f32_e32 v170, v143, v143
	v_and_b32_e32 v137, 0xffff0000, v128
	v_lshlrev_b32_e32 v142, 16, v129
	v_and_b32_e32 v143, 0xffff0000, v129
	v_pk_add_f32 v[128:129], v[6:7], v[180:181]
	v_fmac_f32_e32 v136, 0.5, v130
	v_fmac_f32_e32 v137, 0.5, v131
	v_cvt_pk_bf16_f32 v136, v136, v137
	v_fmac_f32_e32 v142, 0.5, v128
	v_lshlrev_b32_e32 v128, 16, v136
	v_fmac_f32_e32 v143, 0.5, v129
	v_and_b32_e32 v129, 0xffff0000, v136
	v_fmac_f32_e32 v170, v128, v128
	v_cvt_pk_bf16_f32 v137, v142, v143
	v_fmac_f32_e32 v170, v129, v129
	v_lshlrev_b32_e32 v130, 16, v137
	v_pk_add_f32 v[140:141], v[2:3], v[176:177]
	v_pk_add_f32 v[138:139], v[0:1], v[172:173]
	v_and_b32_e32 v131, 0xffff0000, v137
	v_fmac_f32_e32 v170, v130, v130
	v_fmac_f32_e32 v171, 0.5, v138
	v_fmac_f32_e32 v182, 0.5, v139
	v_cvt_pk_bf16_f32 v138, v171, v182
	v_fmac_f32_e32 v183, 0.5, v140
	v_lshlrev_b32_e32 v140, 16, v138
	v_fmac_f32_e32 v170, v131, v131
	v_fmac_f32_e32 v184, 0.5, v141
	v_and_b32_e32 v141, 0xffff0000, v138
	v_fmac_f32_e32 v170, v140, v140
	v_cvt_pk_bf16_f32 v139, v183, v184
	v_fmac_f32_e32 v170, v141, v141
	v_lshlrev_b32_e32 v142, 16, v139
	v_and_b32_e32 v143, 0xffff0000, v139
	v_fmac_f32_e32 v170, v142, v142
	v_fmac_f32_e32 v170, v143, v143
	ds_bpermute_b32 v128, v237, v170
	v_lshl_add_u64 v[130:131], s[28:29], 0, v[174:175]
	v_lshl_add_u64 v[130:131], v[168:169], 1, v[130:131]
	global_store_dwordx4 v[130:131], v[132:135], off sc1
	global_store_dwordx4 v[130:131], v[136:139], off offset:256 sc1
	s_waitcnt lgkmcnt(0)
	v_add_f32_e32 v128, v170, v128
	ds_bpermute_b32 v129, v238, v128
	s_and_saveexec_b64 s[12:13], s[8:9]
	s_cbranch_execz .LBB0_1428
	s_waitcnt lgkmcnt(0)
	v_add_f32_e32 v130, v128, v129
	v_lshl_add_u64 v[128:129], v[166:167], 2, s[14:15]
	global_atomic_add_f32 v[128:129], v130, off offset:704
